# attention loop: K tiles in a 4-slot LDS ring with fragment prefetch before the barrier; P permlane swaps removed by storing V keys in natural order; scalar priority split
# speedup vs baseline: 1.0128x; 1.0128x over previous
; __device__ __forceinline__ int v_st(int k, int c) { const int kk = (k & ~0xC) | ((k & 4) << 1) | ((k & 8) >> 1); return ((kk >> 3) * 4 + (c >> 5)) * 512 + ((kk & 7) * 32 + (c & 31)) * 2; }
; __device__ __forceinline__ int v_rd_base(int lane) { return ((lane & 3) << 3) | (((lane >> 2) & 3) << 6) | (((lane >> 4) & 1) << 5) | (((lane >> 5) & 1) << 8); }
; #define SLOAD(i, k0) do { sr_[i].vs0 = *reinterpret_cast<const bf16x8*>(&Vh[(long)((k0) + sr) * LDQ + sc]); sr_[i].vs1 = *reinterpret_cast<const bf16x8*>(&Vh[(long)((k0) + 32 + sr) * LDQ + sc]); \
;     sr_[i].ks0 = *reinterpret_cast<const bf16x8*>(&Kh[(long)((k0) + kr) * LDQ + kc]); } while (0)
; #define SWRITE(b, i) do { *(bf16x8*)(V_lds + (b) * SHM_V + vst0) = sr_[i].vs0; *(bf16x8*)(V_lds + (b) * SHM_V + vst1) = sr_[i].vs1; \
;     *(bf16x8*)(K_lds + (b) * SHM_K + kst) = sr_[i].ks0; } while (0)
; __device__ __forceinline__ void attn_unit(const bf16_t* __restrict__ Qb, const bf16_t* __restrict__ Kh, const bf16_t* __restrict__ Vh, int seq, char* lds,
;                                           int mode, float* scratch, float lam, float gscale, const float* __restrict__ subg, bf16_t* outp) {
;     ...
;   const int tid = tid_, wid = tid >> 6, lane = tid & 63, r32 = lane & 31, hi = lane >> 5;
;   char* V_lds = lds; char* K_lds = lds + 3 * SHM_V;
;   float* ws = (float*)(lds + 3 * SHM_V + 3 * SHM_K) + wid * 64; float* li_l = ws; float* al_l = ws + 32;
;   float m_reg = 0.f, l_reg = 0; f32x16 o[4] = {}; bf16x8 qr[4];
;   const bf16_t* Qw = Qb + (long)(wid * QBLK + r32) * LDQ + hi * 8;
; #pragma unroll
;   for (int d0 = 0; d0 < 4; ++d0) qr[d0] = *reinterpret_cast<const bf16x8*>(Qw + d0 * 16);
;   const int sr = tid >> 4, sc = (tid & 15) * 8, vst0 = v_st(sr, sc), vst1 = v_st(32 + sr, sc);
;   const int kr = tid >> 3, kc = (tid & 7) * 8, kst = KSWZ(kr, kc * 2);
;   const int vb0 = (int)(uintptr_t)V_lds + v_rd_base(lane);
;   struct { bf16x8 vs0, vs1, ks0; } sr_[2];
;     ...
;   f32x16 pA0, pA1, pB0, pB1; float alA, alB; bf16x8 pa0, pa1, pa2, pa3; const int NT = seq / KVBLK;
;   constexpr int SE = 0, SO = 1;
;   SLOAD(SE, 0); asm volatile("s_waitcnt vmcnt(0)" ::: "memory"); SWRITE(0, SE); __syncthreads();
;   qkt(pA0, pA1, K_lds, qr, r32, hi, m_reg); partialSM(pA0, pA1, m_reg, alA, true);
;   SLOAD(SO, KVBLK); if (2 < NT) SLOAD(SE, 2 * KVBLK);
;   SWAIT(); SWRITE(1, SO); __syncthreads();
.LBB0_1329:
	v_mov_b32_e32 v56, v214
	s_or_b32 s52, s24, s76
	v_ashrrev_i32_e32 v57, 6, v56
	v_and_b32_e32 v165, 31, v56
	v_lshlrev_b32_e32 v152, 5, v57
	s_lshl_b64 s[0:1], s[52:53], 1
	v_or_b32_e32 v0, v152, v165
	s_add_u32 s58, s74, s0
	v_ashrrev_i32_e32 v1, 31, v0
	s_addc_u32 s59, s75, s1
	v_bfe_u32 v164, v56, 5, 1
	v_lshlrev_b64 v[0:1], 10, v[0:1]
	v_lshl_add_u64 v[0:1], s[58:59], 0, v[0:1]
	v_lshlrev_b32_e32 v178, 4, v164
	v_lshl_add_u64 v[0:1], v[0:1], 0, v[178:179]
	global_load_dwordx4 v[124:127], v[0:1], off
	global_load_dwordx4 v[120:123], v[0:1], off offset:32
	global_load_dwordx4 v[116:119], v[0:1], off offset:64
	global_load_dwordx4 v[112:115], v[0:1], off offset:96
	v_ashrrev_i32_e32 v0, 4, v56
	v_and_b32_e32 v1, 0xfffff0, v0
	v_lshlrev_b32_e32 v3, 1, v0
	v_lshlrev_b32_e32 v12, 3, v56
	v_and_or_b32 v1, v3, 8, v1
	v_lshrrev_b32_e32 v3, 1, v0
	v_lshrrev_b32_e32 v1, 1, v1
	v_bfe_u32 v5, v12, 5, 2
	v_and_b32_e32 v4, 3, v0
	v_or_b32_e32 v1, v1, v5
	v_and_or_b32 v3, v3, 4, v4
	v_lshlrev_b32_e32 v6, 4, v56
	v_lshlrev_b32_e32 v1, 9, v1
	v_lshlrev_b32_e32 v3, 6, v3
	v_and_b32_e32 v7, 48, v6
	v_add_u32_e32 v4, 32, v0
	v_or3_b32 v168, v1, v3, v7
	v_and_b32_e32 v1, 0xfffff0, v4
	v_lshlrev_b32_e32 v8, 1, v4
	v_and_or_b32 v1, v8, 8, v1
	v_lshrrev_b32_e32 v1, 1, v1
	v_or_b32_e32 v1, v1, v5
	v_lshlrev_b32_e32 v1, 9, v1
	v_ashrrev_i32_e32 v8, 3, v56
	v_or3_b32 v169, v1, v3, v7
	v_lshrrev_b32_e32 v232, 7, v56
	v_lshlrev_b32_e32 v232, 11, v232
	v_bfe_u32 v233, v56, 2, 2
	v_lshl_or_b32 v232, v233, 9, v232
	v_bfe_u32 v233, v56, 4, 3
	v_lshl_or_b32 v232, v233, 6, v232
	v_and_b32_e32 v233, 3, v56
	v_lshl_or_b32 v168, v233, 4, v232
	v_add_u32_e32 v169, 0x2000, v168
	v_lshlrev_b32_e32 v1, 7, v8
	v_and_b32_e32 v10, 0x70, v6
	v_and_b32_e32 v3, 0x70, v56
	v_bitop3_b32 v170, v10, v1, v3 bitop3:0xde
	v_ashrrev_i32_e32 v1, 31, v0
	v_ashrrev_i32_e32 v5, 31, v4
	s_add_u32 s20, s77, s0
	v_and_b32_e32 v2, 0x78, v12
	v_lshlrev_b64 v[48:49], 10, v[0:1]
	v_lshlrev_b64 v[4:5], 10, v[4:5]
	v_ashrrev_i32_e32 v9, 31, v8
	s_addc_u32 s21, s78, s1
	v_lshl_add_u64 v[0:1], s[18:19], 0, v[48:49]
	v_lshlrev_b32_e32 v6, 1, v2
	v_mov_b32_e32 v7, v179
	v_lshl_add_u64 v[4:5], s[18:19], 0, v[4:5]
	v_lshlrev_b64 v[50:51], 10, v[8:9]
	v_lshl_add_u64 v[52:53], v[0:1], 0, v[6:7]
	v_lshl_add_u64 v[4:5], v[4:5], 0, v[6:7]
	v_lshl_add_u64 v[8:9], s[20:21], 0, v[50:51]
	v_mov_b32_e32 v11, v179
	global_load_dwordx4 v[0:3], v[52:53], off
	v_lshl_add_u64 v[54:55], v[8:9], 0, v[10:11]
	global_load_dwordx4 v[4:7], v[4:5], off
	v_lshlrev_b32_e32 v64, 7, v165
	global_load_dwordx4 v[8:11], v[54:55], off
	v_and_b32_e32 v65, 0x70, v12
	v_add_u32_e32 v58, 0, v168
	v_add_u32_e32 v59, 0, v169
	v_bitop3_b32 v173, v178, v64, v65 bitop3:0xde
	s_waitcnt vmcnt(0)
	v_add_u32_e32 v171, 0, v170
	v_mov_b64_e32 v[32:33], s[36:37]
	v_mov_b64_e32 v[34:35], s[38:39]
	v_mov_b64_e32 v[36:37], s[40:41]
	v_mov_b64_e32 v[38:39], s[42:43]
	v_mov_b64_e32 v[40:41], s[44:45]
	v_mov_b64_e32 v[42:43], s[46:47]
	v_mov_b64_e32 v[44:45], s[48:49]
	v_mov_b64_e32 v[46:47], s[50:51]
	s_mov_b32 s0, 0x18000
	s_waitcnt vmcnt(2)
	ds_write_b128 v58, v[0:3]
	s_waitcnt vmcnt(1)
	ds_write_b128 v59, v[4:7]
	v_add_u32_e32 v4, 0, v173
	s_waitcnt vmcnt(0)
	ds_write_b128 v171, v[8:11] offset:49152
	s_waitcnt lgkmcnt(0)
	s_barrier
	ds_read_b128 v[0:3], v4 offset:49152
	ds_read_b128 v[60:63], v4 offset:53248
	s_waitcnt lgkmcnt(1)
	v_mfma_f32_32x32x16_bf16 v[16:31], v[0:3], v[124:127], v[32:47]
	s_waitcnt lgkmcnt(0)
	v_mfma_f32_32x32x16_bf16 v[0:15], v[60:63], v[124:127], v[32:47]
	s_nop 6
	v_or_b32_e32 v32, 32, v178
	v_bitop3_b32 v175, v32, v64, v65 bitop3:0xde
	v_add_u32_e32 v36, 0, v175
	ds_read_b128 v[32:35], v36 offset:49152
	ds_read_b128 v[36:39], v36 offset:53248
	s_waitcnt lgkmcnt(1)
	v_mfma_f32_32x32x16_bf16 v[16:31], v[32:35], v[120:123], v[16:31]
	v_or_b32_e32 v32, 64, v178
	v_bitop3_b32 v174, v32, v64, v65 bitop3:0xde
	s_waitcnt lgkmcnt(0)
	v_mfma_f32_32x32x16_bf16 v[0:15], v[36:39], v[120:123], v[0:15]
	v_add_u32_e32 v36, 0, v174
	ds_read_b128 v[32:35], v36 offset:49152
	ds_read_b128 v[36:39], v36 offset:53248
	s_waitcnt lgkmcnt(1)
	v_mfma_f32_32x32x16_bf16 v[16:31], v[32:35], v[116:119], v[16:31]
	v_or_b32_e32 v32, 0x60, v178
	v_bitop3_b32 v176, v32, v64, v65 bitop3:0xde
	s_waitcnt lgkmcnt(0)
	v_mfma_f32_32x32x16_bf16 v[0:15], v[36:39], v[116:119], v[0:15]
	v_add_u32_e32 v36, 0, v176
	ds_read_b128 v[32:35], v36 offset:49152
	ds_read_b128 v[36:39], v36 offset:53248
	s_waitcnt lgkmcnt(1)
	v_mfma_f32_32x32x16_bf16 v[16:31], v[32:35], v[112:115], v[16:31]
	s_waitcnt lgkmcnt(0)
	v_mfma_f32_32x32x16_bf16 v[0:15], v[36:39], v[112:115], v[0:15]
	s_nop 9
	v_max_f32_e32 v32, v17, v17
	v_max_f32_e32 v33, v16, v16
	v_max_f32_e32 v32, v33, v32
	v_max3_f32 v32, v32, v18, v19
	v_max3_f32 v32, v32, v20, v21
	v_max3_f32 v32, v32, v22, v23
	v_max3_f32 v32, v32, v24, v25
	v_max3_f32 v32, v32, v26, v27
	v_max3_f32 v32, v32, v28, v29
	v_max3_f32 v32, v32, v30, v31
	v_max3_f32 v32, v32, v0, v1
	v_max3_f32 v32, v32, v2, v3
	v_max3_f32 v32, v32, v4, v5
	v_max3_f32 v32, v32, v6, v7
	v_max3_f32 v32, v32, v8, v9
	v_max3_f32 v32, v32, v10, v11
	v_max3_f32 v32, v32, v12, v13
	v_max3_f32 v36, v32, v14, v15
	v_add_co_u32_e32 v32, vcc, s63, v52
	v_mov_b32_e32 v37, v36
	s_nop 0
	v_addc_co_u32_e32 v33, vcc, 0, v53, vcc
	v_add_co_u32_e32 v38, vcc, s0, v52
	s_mov_b32 s0, 0x20000
	s_nop 0
	v_addc_co_u32_e32 v39, vcc, 0, v53, vcc
	v_add_co_u32_e32 v42, vcc, s63, v54
	global_load_dwordx4 v[32:35], v[32:33], off
	s_nop 0
	v_addc_co_u32_e32 v43, vcc, 0, v55, vcc
	v_add_co_u32_e32 v46, vcc, s0, v52
	global_load_dwordx4 v[42:45], v[42:43], off
	s_nop 0
	v_addc_co_u32_e32 v47, vcc, 0, v53, vcc
	global_load_dwordx4 v[128:131], v[46:47], off
	v_add_co_u32_e32 v46, vcc, 0x28000, v52
	global_load_dwordx4 v[38:41], v[38:39], off
	s_nop 0
	v_addc_co_u32_e32 v47, vcc, 0, v53, vcc
	global_load_dwordx4 v[132:135], v[46:47], off
	v_add_co_u32_e32 v46, vcc, 0x20000, v54
	v_permlane32_swap_b32_e32 v36, v37
	s_nop 0
	v_addc_co_u32_e32 v47, vcc, 0, v55, vcc
	global_load_dwordx4 v[136:139], v[46:47], off
	s_waitcnt vmcnt(3)
	v_cmp_lt_i32_e32 vcc, 3, v57
	s_waitcnt vmcnt(5)
	ds_write_b128 v58, v[32:35] offset:16384
	s_waitcnt vmcnt(2)
	ds_write_b128 v59, v[38:41] offset:16384
	ds_write_b128 v171, v[42:45] offset:57344
	s_waitcnt lgkmcnt(0)
	s_barrier
; #define SLOAD(i, k0) do { sr_[i].vs0 = *reinterpret_cast<const bf16x8*>(&Vh[(long)((k0) + sr) * LDQ + sc]); sr_[i].vs1 = *reinterpret_cast<const bf16x8*>(&Vh[(long)((k0) + 32 + sr) * LDQ + sc]); \
;     sr_[i].ks0 = *reinterpret_cast<const bf16x8*>(&Kh[(long)((k0) + kr) * LDQ + kc]); } while (0)
; #define SWRITE(b, i) do { *(bf16x8*)(V_lds + (b) * SHM_V + vst0) = sr_[i].vs0; *(bf16x8*)(V_lds + (b) * SHM_V + vst1) = sr_[i].vs1; \
;     *(bf16x8*)(K_lds + (b) * SHM_K + kst) = sr_[i].ks0; } while (0)
; #define SWAIT() asm volatile("s_waitcnt vmcnt(3)" ::: "memory")
; __device__ __forceinline__ void partialSM(f32x16& p0, f32x16& p1, float& m_ref, float& alpha, bool first) {
;   constexpr float THRL = THR * 1.4426950408889634f;
;   float pmax = p0[0];
; #pragma unroll
;   for (int r = 1; r < 16; ++r) pmax = fmaxf(pmax, p0[r]);
; #pragma unroll
;   for (int r = 0; r < 16; ++r) pmax = fmaxf(pmax, p1[r]);
;   { auto rr = __builtin_amdgcn_permlane32_swap(__float_as_uint(pmax), __float_as_uint(pmax), false, false);
;     pmax = fmaxf(__uint_as_float(rr[0]), __uint_as_float(rr[1])); }
;   if (__builtin_expect(!first && __all(pmax <= THRL), 1)) { alpha = 1.f; }
;   else { const float dl = first ? pmax : fmaxf(pmax, 0.f); m_ref += dl; alpha = first ? 1.f : __builtin_amdgcn_exp2f(-dl);
; #pragma unroll
;     for (int r = 0; r < 16; ++r) { p0[r] -= dl; p1[r] -= dl; } }
; #pragma unroll
;   for (int r = 0; r < 16; ++r) p0[r] = __builtin_amdgcn_exp2f(p0[r]);
; __device__ __forceinline__ void attn_unit(const bf16_t* __restrict__ Qb, const bf16_t* __restrict__ Kh, const bf16_t* __restrict__ Vh, int seq, char* lds,
;                                           int mode, float* scratch, float lam, float gscale, const float* __restrict__ subg, bf16_t* outp) {
;     ...
;   f32x16 pA0, pA1, pB0, pB1; float alA, alB; bf16x8 pa0, pa1, pa2, pa3; const int NT = seq / KVBLK;
;   constexpr int SE = 0, SO = 1;
;   SLOAD(SE, 0); asm volatile("s_waitcnt vmcnt(0)" ::: "memory"); SWRITE(0, SE); __syncthreads();
;   qkt(pA0, pA1, K_lds, qr, r32, hi, m_reg); partialSM(pA0, pA1, m_reg, alA, true);
;   SLOAD(SO, KVBLK); if (2 < NT) SLOAD(SE, 2 * KVBLK);
;   SWAIT(); SWRITE(1, SO); __syncthreads();
;   int bp = 0, bc = 1, bn = 2;
;     ...
;   if (wid >= 4) __builtin_amdgcn_s_setprio(1);
	s_and_saveexec_b64 s[20:21], vcc
	s_setprio 1
	s_or_b64 exec, exec, s[20:21]
	v_max_f32_e32 v33, v37, v37
	v_max_f32_e32 v34, v36, v36
	v_max_f32_e32 v33, v34, v33
	s_xor_b64 s[72:73], s[4:5], -1
	s_add_i32 s1, 0, 0x14000
	v_sub_f32_e32 v64, v0, v33
	v_and_b32_e32 v0, 15, v56
	v_and_b32_e32 v32, 63, v56
	v_sub_f32_e32 v16, v16, v33
	v_sub_f32_e32 v17, v17, v33
	s_cmp_lg_u32 0, -1
	v_sub_f32_e32 v65, v1, v33
	v_lshlrev_b32_e32 v0, 4, v0
	v_mov_b32_e32 v1, v179
	v_sub_f32_e32 v18, v18, v33
	v_exp_f32_e32 v160, v16
	v_exp_f32_e32 v192, v17
	v_and_b32_e32 v16, 0x3fffffc0, v56
	v_lshlrev_b32_e32 v17, 4, v32
	s_cselect_b32 s4, 0, 0
	v_lshl_add_u64 v[0:1], v[48:49], 0, v[0:1]
	s_add_i32 s52, s71, s24
	v_sub_f32_e32 v19, v19, v33
	v_sub_f32_e32 v20, v20, v33
	v_sub_f32_e32 v21, v21, v33
	v_sub_f32_e32 v22, v22, v33
	v_sub_f32_e32 v23, v23, v33
	v_sub_f32_e32 v24, v24, v33
	v_sub_f32_e32 v25, v25, v33
	v_sub_f32_e32 v26, v26, v33
	v_sub_f32_e32 v27, v27, v33
	v_sub_f32_e32 v28, v28, v33
	v_sub_f32_e32 v29, v29, v33
	v_sub_f32_e32 v30, v30, v33
	v_sub_f32_e32 v31, v31, v33
	v_exp_f32_e32 v151, v18
	v_lshl_add_u32 v166, v16, 2, s1
	v_lshlrev_b32_e32 v16, 3, v32
	v_and_b32_e32 v17, 0xc0, v17
	v_lshlrev_b32_e32 v18, 1, v32
	v_lshl_add_u64 v[154:155], s[28:29], 0, v[0:1]
	v_and_b32_e32 v0, 7, v56
	s_lshl_b64 s[20:21], s[52:53], 1
	v_exp_f32_e32 v161, v19
	v_exp_f32_e32 v149, v20
	v_exp_f32_e32 v159, v21
	v_exp_f32_e32 v148, v22
	v_exp_f32_e32 v150, v23
	v_exp_f32_e32 v145, v24
	v_exp_f32_e32 v147, v25
	v_exp_f32_e32 v143, v26
	v_exp_f32_e32 v146, v27
	v_exp_f32_e32 v141, v28
	v_exp_f32_e32 v144, v29
	v_exp_f32_e32 v140, v30
	v_exp_f32_e32 v142, v31
	v_and_or_b32 v17, v16, 24, v17
	v_and_b32_e32 v18, 32, v18
	v_and_b32_e32 v16, 0x100, v16
	v_lshlrev_b32_e32 v0, 4, v0
	v_mov_b32_e32 v1, v179
	s_add_u32 s20, s10, s20
	v_or3_b32 v16, v17, v18, v16
	v_sub_f32_e32 v79, v15, v33
	v_sub_f32_e32 v78, v14, v33
	v_lshl_add_u64 v[0:1], v[50:51], 0, v[0:1]
	s_addc_u32 s21, s11, s21
	v_mov_b32_e32 v14, v179
	v_mov_b32_e32 v15, v179
	v_add_u32_e32 v177, s4, v16
	v_add_f32_e32 v181, 0, v33
	v_sub_f32_e32 v77, v13, v33
	v_sub_f32_e32 v76, v12, v33
	v_sub_f32_e32 v75, v11, v33
	v_sub_f32_e32 v74, v10, v33
	v_sub_f32_e32 v73, v9, v33
	v_sub_f32_e32 v72, v8, v33
	v_sub_f32_e32 v71, v7, v33
	v_sub_f32_e32 v70, v6, v33
	v_sub_f32_e32 v69, v5, v33
	v_sub_f32_e32 v68, v4, v33
	v_sub_f32_e32 v67, v3, v33
	v_sub_f32_e32 v66, v2, v33
	v_cmp_gt_u32_e64 s[4:5], 32, v32
	v_lshl_add_u64 v[156:157], s[20:21], 0, v[0:1]
	v_mov_b32_e32 v0, v179
	v_mov_b32_e32 v1, v179
	v_mov_b32_e32 v2, v179
	v_mov_b32_e32 v3, v179
	v_mov_b32_e32 v4, v179
	v_mov_b32_e32 v5, v179
	v_mov_b32_e32 v6, v179
	v_mov_b32_e32 v7, v179
	v_mov_b32_e32 v8, v179
	v_mov_b32_e32 v9, v179
	v_mov_b32_e32 v10, v179
	v_mov_b32_e32 v11, v179
	v_mov_b32_e32 v12, v179
	v_mov_b32_e32 v13, v179
	v_mov_b64_e32 v[62:63], v[14:15]
	v_mov_b64_e32 v[46:47], v[14:15]
	v_mov_b64_e32 v[30:31], v[14:15]
	s_mov_b32 s0, 2
	s_mov_b32 s1, 1
	s_mov_b32 s2, 0
	v_lshl_add_u32 v153, v165, 2, v166
	v_mov_b32_e32 v167, 0
	v_mov_b32_e32 v186, 1.0
	v_mov_b64_e32 v[60:61], v[12:13]
	v_mov_b64_e32 v[58:59], v[10:11]
	v_mov_b64_e32 v[56:57], v[8:9]
	v_mov_b64_e32 v[54:55], v[6:7]
	v_mov_b64_e32 v[52:53], v[4:5]
	v_mov_b64_e32 v[50:51], v[2:3]
	v_mov_b64_e32 v[48:49], v[0:1]
	v_mov_b64_e32 v[44:45], v[12:13]
	v_mov_b64_e32 v[42:43], v[10:11]
	v_mov_b64_e32 v[40:41], v[8:9]
	v_mov_b64_e32 v[38:39], v[6:7]
	v_mov_b64_e32 v[36:37], v[4:5]
	v_mov_b64_e32 v[34:35], v[2:3]
	v_mov_b64_e32 v[32:33], v[0:1]
	v_mov_b64_e32 v[28:29], v[12:13]
	v_mov_b64_e32 v[26:27], v[10:11]
	v_mov_b64_e32 v[24:25], v[8:9]
	v_mov_b64_e32 v[22:23], v[6:7]
	v_mov_b64_e32 v[20:21], v[4:5]
	v_mov_b64_e32 v[18:19], v[2:3]
	v_mov_b64_e32 v[16:17], v[0:1]
	s_mov_b32 s52, 1
	v_exp_f32_e32 v80, v64
	v_exp_f32_e32 v81, v65
	v_exp_f32_e32 v82, v66
	v_exp_f32_e32 v83, v67
	v_exp_f32_e32 v84, v68
	v_exp_f32_e32 v85, v69
	v_exp_f32_e32 v86, v70
	v_exp_f32_e32 v87, v71
	v_exp_f32_e32 v88, v72
	v_exp_f32_e32 v89, v73
	v_exp_f32_e32 v90, v74
	v_exp_f32_e32 v91, v75
	v_exp_f32_e32 v92, v76
	v_exp_f32_e32 v93, v77
	v_exp_f32_e32 v94, v78
	v_exp_f32_e32 v95, v79
	v_mov_b32_e32 v64, v160
	v_mov_b32_e32 v65, v192
	v_mov_b32_e32 v66, v151
	v_mov_b32_e32 v67, v161
	v_mov_b32_e32 v68, v149
	v_mov_b32_e32 v69, v159
	v_mov_b32_e32 v70, v148
	v_mov_b32_e32 v71, v150
	v_mov_b32_e32 v72, v145
	v_mov_b32_e32 v73, v147
	v_mov_b32_e32 v74, v143
	v_mov_b32_e32 v75, v146
	v_mov_b32_e32 v76, v141
	v_mov_b32_e32 v77, v144
	v_mov_b32_e32 v78, v140
	v_mov_b32_e32 v79, v142
	v_mov_b32_e32 v235, v186
	v_xor_b32_e32 v236, 0x80000000, v181
	v_mov_b32_e32 v237, v236
	v_mov_b32_e32 v238, v236
	v_mov_b32_e32 v239, v236
	v_mov_b32_e32 v240, v236
	v_mov_b32_e32 v241, v236
	v_mov_b32_e32 v242, v236
	v_mov_b32_e32 v243, v236
	v_mov_b32_e32 v244, v236
	v_mov_b32_e32 v245, v236
	v_mov_b32_e32 v246, v236
	v_mov_b32_e32 v247, v236
	v_mov_b32_e32 v248, v236
	v_mov_b32_e32 v249, v236
	v_mov_b32_e32 v250, v236
	v_mov_b32_e32 v251, v236
	v_readfirstlane_b32 s24, v156
	v_readfirstlane_b32 s25, v157
	s_nop 1
	v_subrev_u32_e32 v232, s24, v156
	v_subrev_u32_e32 v233, s24, v154
	v_add_u32_e32 v233, 0x2000000, v233
	v_add_u32_e32 v234, 0x8000, v233
	s_add_u32 s24, s24, s16
	s_addc_u32 s25, s25, s17
	s_add_u32 s24, s24, 0x15c30000
	s_addc_u32 s25, s25, 0
	s_waitcnt vmcnt(0)
	v_add_u32_e32 v217, 0x4000, v170
	ds_write_b128 v217, v[136:139] offset:49152
	global_load_dwordx4 v[136:139], v232, s[24:25]
	v_add_u32_e32 v232, 0x10000, v232
	v_readfirstlane_b32 s58, v214
	s_setprio 0
	s_lshr_b32 s58, s58, 8
	s_cmp_lg_u32 s58, 1
	s_cbranch_scc1 .Lat_noprio
	s_setprio 1
; #define SBAR() __builtin_amdgcn_sched_barrier(0)
; #define SLOAD(i, k0) do { sr_[i].vs0 = *reinterpret_cast<const bf16x8*>(&Vh[(long)((k0) + sr) * LDQ + sc]); sr_[i].vs1 = *reinterpret_cast<const bf16x8*>(&Vh[(long)((k0) + 32 + sr) * LDQ + sc]); \
;     sr_[i].ks0 = *reinterpret_cast<const bf16x8*>(&Kh[(long)((k0) + kr) * LDQ + kc]); } while (0)
; #define SWAIT() asm volatile("s_waitcnt vmcnt(3)" ::: "memory")
; __device__ __forceinline__ void finishSM(f32x16& p0, f32x16& p1, float alpha, float& l_reg, bf16x8& pa0, bf16x8& pa1, bf16x8& pa2, bf16x8& pa3) {
; #pragma unroll
;   for (int r = 0; r < 16; ++r) p1[r] = __builtin_amdgcn_exp2f(p1[r]);
;   float ps = 0;
; #pragma unroll
;   for (int r = 0; r < 16; ++r) ps += p0[r];
; #pragma unroll
;   for (int r = 0; r < 16; ++r) ps += p1[r];
;   { auto rr = __builtin_amdgcn_permlane32_swap(__float_as_uint(ps), __float_as_uint(ps), false, false);
;     ps = __uint_as_float(rr[0]) + __uint_as_float(rr[1]); }
;   l_reg = l_reg * alpha + ps;
;     ...
;   PK4(p0, 0, pa0); PK4(p0, 8, pa1); PK4(p1, 0, pa2); PK4(p1, 8, pa3);
;     ...
; }
; __device__ __forceinline__ void qkt(f32x16& p0, f32x16& p1, const char* Ks, const bf16x8* qr, int r32, int hi, float m_ref) {
; #pragma unroll
;   for (int r = 0; r < 16; ++r) { p0[r] = -m_ref; p1[r] = -m_ref; }
; #pragma unroll
;   for (int d0 = 0; d0 < 4; ++d0) { const int cb = (d0 * 16 + hi * 8) * 2;
;     bf16x8 b0 = *reinterpret_cast<const bf16x8*>(Ks + KSWZ(r32, cb));
;     bf16x8 b1 = *reinterpret_cast<const bf16x8*>(Ks + KSWZ(32 + r32, cb));
;     p0 = __builtin_amdgcn_mfma_f32_32x32x16_bf16(b0, qr[d0], p0, 0, 0, 0);
;     p1 = __builtin_amdgcn_mfma_f32_32x32x16_bf16(b1, qr[d0], p1, 0, 0, 0); }
; __device__ __forceinline__ void attn_unit(const bf16_t* __restrict__ Qb, const bf16_t* __restrict__ Kh, const bf16_t* __restrict__ Vh, int seq, char* lds,
;                                           int mode, float* scratch, float lam, float gscale, const float* __restrict__ subg, bf16_t* outp) {
;     ...
;   for (int j = 1; j + 1 < NT; j += 2) {
;     SBAR(); qkt(pB0, pB1, K_lds + bc * SHM_K, qr, r32, hi, m_reg);
;     finishSM(pA0, pA1, alA, l_reg, pa0, pa1, pa2, pa3); SBAR();
;     SLOAD(SO, (j + 2) * KVBLK); SBAR();
;     pv_d0(o, vb0 + bp * SHM_V, pa0, pa1, pa2, pa3); partialSM(pB0, pB1, m_reg, alB, false);
;     SWAIT(); SWRITE(bn, SE);
;     RESC(alB); __syncthreads(); ROT3();
.Lat_noprio:
	s_waitcnt lgkmcnt(0)
	s_barrier
	s_mov_b32 s58, 0x2000
	v_add_u32_e32 v218, s58, v173
	ds_read_b128 v[182:185], v218 offset:49152
	ds_read_b128 v[186:189], v218 offset:53248
	v_add_u32_e32 v218, s58, v175
	ds_read_b128 v[190:193], v218 offset:49152
	ds_read_b128 v[194:197], v218 offset:53248
	v_add_u32_e32 v218, s58, v174
	ds_read_b128 v[198:201], v218 offset:49152
	ds_read_b128 v[202:205], v218 offset:53248
	v_add_u32_e32 v218, s58, v176
	ds_read_b128 v[206:209], v218 offset:49152
	ds_read_b128 v[210:213], v218 offset:53248
.Lat_loop:
	s_mov_b32 s21, 0
	global_load_dwordx4 v[140:143], v233, s[24:25]
	global_load_dwordx4 v[144:147], v234, s[24:25]
	global_load_dwordx4 v[148:151], v232, s[24:25]
	s_add_u32 s24, s24, 0x10000
	s_addc_u32 s25, s25, 0
	v_add_f32_e32 v159, v64, v65
	v_cvt_pk_bf16_f32 v64, v64, v65
	v_add_f32_e32 v160, v66, v67
	v_cvt_pk_bf16_f32 v65, v66, v67
	v_add_f32_e32 v159, v68, v159
	s_waitcnt lgkmcnt(7)
	v_mfma_f32_32x32x16_bf16 v[96:111], v[182:185], v[124:127], v[236:251]
	v_add_f32_e32 v160, v69, v160
	v_cvt_pk_bf16_f32 v66, v68, v69
	v_add_f32_e32 v159, v70, v159
	v_add_f32_e32 v160, v71, v160
	v_cvt_pk_bf16_f32 v67, v70, v71
	v_add_f32_e32 v159, v72, v159
	s_waitcnt lgkmcnt(6)
	v_mfma_f32_32x32x16_bf16 v[236:251], v[186:189], v[124:127], v[236:251]
	s_lshl_b32 s79, s0, 14
	s_add_i32 s20, s52, 2
	s_and_b32 s20, s20, 3
	s_lshl_b32 s20, s20, 13
	s_waitcnt vmcnt(3)
	v_add_u32_e32 v217, s79, v168
	ds_write_b128 v217, v[128:131]
	v_add_u32_e32 v218, s79, v169
	ds_write_b128 v218, v[132:135]
	v_add_u32_e32 v217, s20, v170
	ds_write_b128 v217, v[136:139] offset:49152
	v_add_f32_e32 v160, v73, v160
	v_cvt_pk_bf16_f32 v68, v72, v73
	v_add_f32_e32 v159, v74, v159
	v_add_f32_e32 v160, v75, v160
	v_cvt_pk_bf16_f32 v69, v74, v75
	s_waitcnt lgkmcnt(8)
	v_mfma_f32_32x32x16_bf16 v[96:111], v[190:193], v[120:123], v[96:111]
	v_add_f32_e32 v159, v76, v159
	v_add_f32_e32 v160, v77, v160
	v_cvt_pk_bf16_f32 v70, v76, v77
	v_add_f32_e32 v159, v78, v159
	v_add_f32_e32 v160, v79, v160
	v_cvt_pk_bf16_f32 v71, v78, v79
	s_waitcnt lgkmcnt(7)
	v_mfma_f32_32x32x16_bf16 v[236:251], v[194:197], v[120:123], v[236:251]
	s_lshl_b32 s59, s2, 14
	v_add_u32_e32 v172, s59, v177
	ds_read_b64_tr_b16 v[182:183], v172 offset:0x0
	ds_read_b64_tr_b16 v[184:185], v172 offset:0x800
	ds_read_b64_tr_b16 v[186:187], v172 offset:0x1000
	ds_read_b64_tr_b16 v[188:189], v172 offset:0x1800
	ds_read_b64_tr_b16 v[190:191], v172 offset:0x2000
	ds_read_b64_tr_b16 v[192:193], v172 offset:0x2800
	ds_read_b64_tr_b16 v[194:195], v172 offset:0x3000
	ds_read_b64_tr_b16 v[196:197], v172 offset:0x3800
	v_add_f32_e32 v159, v80, v159
	v_add_f32_e32 v160, v81, v160
	v_cvt_pk_bf16_f32 v72, v80, v81
	v_add_f32_e32 v159, v82, v159
	v_add_f32_e32 v160, v83, v160
	v_cvt_pk_bf16_f32 v73, v82, v83
	s_waitcnt lgkmcnt(14)
	v_mfma_f32_32x32x16_bf16 v[96:111], v[198:201], v[116:119], v[96:111]
	v_add_f32_e32 v159, v84, v159
	v_add_f32_e32 v160, v85, v160
	v_cvt_pk_bf16_f32 v74, v84, v85
	v_add_f32_e32 v159, v86, v159
	v_add_f32_e32 v160, v87, v160
	v_cvt_pk_bf16_f32 v75, v86, v87
	s_waitcnt lgkmcnt(13)
	v_mfma_f32_32x32x16_bf16 v[236:251], v[202:205], v[116:119], v[236:251]
	s_waitcnt lgkmcnt(8)
	ds_read_b64_tr_b16 v[198:199], v172 offset:0x200
	ds_read_b64_tr_b16 v[200:201], v172 offset:0xa00
	ds_read_b64_tr_b16 v[202:203], v172 offset:0x1200
	ds_read_b64_tr_b16 v[204:205], v172 offset:0x1a00
	v_add_f32_e32 v159, v88, v159
	v_add_f32_e32 v160, v89, v160
	v_cvt_pk_bf16_f32 v76, v88, v89
	v_add_f32_e32 v159, v90, v159
	v_add_f32_e32 v160, v91, v160
	v_cvt_pk_bf16_f32 v77, v90, v91
	v_add_f32_e32 v159, v92, v159
	v_mfma_f32_32x32x16_bf16 v[96:111], v[206:209], v[112:115], v[96:111]
	ds_read_b64_tr_b16 v[206:207], v172 offset:0x2200
	ds_read_b64_tr_b16 v[208:209], v172 offset:0x2a00
	v_add_f32_e32 v160, v93, v160
	v_cvt_pk_bf16_f32 v78, v92, v93
	v_add_f32_e32 v159, v94, v159
	v_add_f32_e32 v160, v95, v160
	v_cvt_pk_bf16_f32 v79, v94, v95
	v_add_f32_e32 v159, v159, v160
	v_fma_f32 v167, v167, v235, v159
	v_mfma_f32_32x32x16_bf16 v[236:251], v[210:213], v[112:115], v[236:251]
	s_waitcnt lgkmcnt(12)
	v_mfma_f32_32x32x16_bf16 v[0:15], v[64:67], v[182:185], v[0:15]
	ds_read_b64_tr_b16 v[210:211], v172 offset:0x3200
	ds_read_b64_tr_b16 v[212:213], v172 offset:0x3a00
	v_max3_f32 v161, v96, v97, v98
	v_max3_f32 v161, v161, v99, v100
	v_max3_f32 v161, v161, v101, v102
	v_max3_f32 v161, v161, v103, v104
	s_waitcnt lgkmcnt(12)
	v_mfma_f32_32x32x16_bf16 v[0:15], v[68:71], v[186:189], v[0:15]
	ds_read_b64_tr_b16 v[182:183], v172 offset:0x400
	ds_read_b64_tr_b16 v[184:185], v172 offset:0xc00
	v_max3_f32 v161, v161, v105, v106
	v_max3_f32 v161, v161, v107, v108
	v_max3_f32 v161, v161, v109, v110
	v_max_f32_e32 v161, v161, v111
	s_waitcnt lgkmcnt(12)
	v_mfma_f32_32x32x16_bf16 v[0:15], v[72:75], v[190:193], v[0:15]
	ds_read_b64_tr_b16 v[186:187], v172 offset:0x1400
	ds_read_b64_tr_b16 v[188:189], v172 offset:0x1c00
	v_max3_f32 v216, v236, v237, v238
	v_max3_f32 v216, v216, v239, v240
	v_max3_f32 v216, v216, v241, v242
	v_max3_f32 v216, v216, v243, v244
	s_waitcnt lgkmcnt(12)
	v_mfma_f32_32x32x16_bf16 v[0:15], v[76:79], v[194:197], v[0:15]
	ds_read_b64_tr_b16 v[190:191], v172 offset:0x2400
	ds_read_b64_tr_b16 v[192:193], v172 offset:0x2c00
	v_max3_f32 v216, v216, v245, v246
	v_max3_f32 v216, v216, v247, v248
	v_max3_f32 v216, v216, v249, v250
	v_max_f32_e32 v216, v216, v251
	v_max_f32_e32 v161, v161, v216
	v_cmp_ge_f32_e32 vcc, s66, v161
	s_cmp_eq_u64 vcc, exec
	s_cbranch_scc0 .Lat_rare0
	v_mov_b32_e32 v158, 1.0
; #define SBAR() __builtin_amdgcn_sched_barrier(0)
; #define SLOAD(i, k0) do { sr_[i].vs0 = *reinterpret_cast<const bf16x8*>(&Vh[(long)((k0) + sr) * LDQ + sc]); sr_[i].vs1 = *reinterpret_cast<const bf16x8*>(&Vh[(long)((k0) + 32 + sr) * LDQ + sc]); \
;     sr_[i].ks0 = *reinterpret_cast<const bf16x8*>(&Kh[(long)((k0) + kr) * LDQ + kc]); } while (0)
; #define SWRITE(b, i) do { *(bf16x8*)(V_lds + (b) * SHM_V + vst0) = sr_[i].vs0; *(bf16x8*)(V_lds + (b) * SHM_V + vst1) = sr_[i].vs1; \
;     *(bf16x8*)(K_lds + (b) * SHM_K + kst) = sr_[i].ks0; } while (0)
; #define SWAIT() asm volatile("s_waitcnt vmcnt(3)" ::: "memory")
; #define ROT3() do { const int t_ = bp; bp = bc; bc = bn; bn = t_; } while (0)
; template <int D0> __device__ __forceinline__ void pv_one(f32x16& od, int vb, bf16x8 pa0, bf16x8 pa1, bf16x8 pa2, bf16x8 pa3) {
;   const s16x4 l0 = tr_read<v_rd_off(D0, 0, 0)>(vb), h0 = tr_read<v_rd_off(D0, 0, 1)>(vb), l1 = tr_read<v_rd_off(D0, 1, 0)>(vb), h1 = tr_read<v_rd_off(D0, 1, 1)>(vb);
;   const s16x4 l2 = tr_read<v_rd_off(D0, 2, 0)>(vb), h2 = tr_read<v_rd_off(D0, 2, 1)>(vb), l3 = tr_read<v_rd_off(D0, 3, 0)>(vb), h3 = tr_read<v_rd_off(D0, 3, 1)>(vb);
;   asm volatile("s_waitcnt lgkmcnt(0)" ::: "memory"); SBAR();
;     ...
;   od = __builtin_amdgcn_mfma_f32_32x32x16_bf16(pa0, PK(l0, h0), od, 0, 0, 0);
;   od = __builtin_amdgcn_mfma_f32_32x32x16_bf16(pa1, PK(l1, h1), od, 0, 0, 0);
;   od = __builtin_amdgcn_mfma_f32_32x32x16_bf16(pa2, PK(l2, h2), od, 0, 0, 0);
;   od = __builtin_amdgcn_mfma_f32_32x32x16_bf16(pa3, PK(l3, h3), od, 0, 0, 0);
; __device__ __forceinline__ void attn_unit(const bf16_t* __restrict__ Qb, const bf16_t* __restrict__ Kh, const bf16_t* __restrict__ Vh, int seq, char* lds,
;                                           int mode, float* scratch, float lam, float gscale, const float* __restrict__ subg, bf16_t* outp) {
;     ...
;     pv_d0(o, vb0 + bp * SHM_V, pa0, pa1, pa2, pa3); partialSM(pB0, pB1, m_reg, alB, false);
;     SWAIT(); SWRITE(bn, SE);
;     RESC(alB); __syncthreads(); ROT3();
;     SBAR(); qkt(pA0, pA1, K_lds + bc * SHM_K, qr, r32, hi, m_reg);
;     finishSM(pB0, pB1, alB, l_reg, pa0, pa1, pa2, pa3); SBAR();
;     if (j + 3 < NT) SLOAD(SE, (j + 3) * KVBLK); SBAR();
;     pv_d0(o, vb0 + bp * SHM_V, pa0, pa1, pa2, pa3); partialSM(pA0, pA1, m_reg, alA, false);
;     SWAIT(); SWRITE(bn, SO);
.Lat_back0:
	s_waitcnt lgkmcnt(12)
	v_mfma_f32_32x32x16_bf16 v[48:63], v[64:67], v[198:201], v[48:63]
	ds_read_b64_tr_b16 v[194:195], v172 offset:0x3400
	ds_read_b64_tr_b16 v[196:197], v172 offset:0x3c00
	v_exp_f32_e32 v96, v96
	v_exp_f32_e32 v97, v97
	v_xor_b32_e32 v80, 0x80000000, v181
	v_exp_f32_e32 v98, v98
	s_waitcnt lgkmcnt(12)
	v_mfma_f32_32x32x16_bf16 v[48:63], v[68:71], v[202:205], v[48:63]
	ds_read_b64_tr_b16 v[198:199], v172 offset:0x600
	ds_read_b64_tr_b16 v[200:201], v172 offset:0xe00
	v_exp_f32_e32 v99, v99
	v_exp_f32_e32 v100, v100
	v_mov_b32_e32 v81, v80
	v_exp_f32_e32 v101, v101
	s_waitcnt lgkmcnt(12)
	v_mfma_f32_32x32x16_bf16 v[48:63], v[72:75], v[206:209], v[48:63]
	ds_read_b64_tr_b16 v[202:203], v172 offset:0x1600
	ds_read_b64_tr_b16 v[204:205], v172 offset:0x1e00
	v_exp_f32_e32 v102, v102
	v_exp_f32_e32 v103, v103
	v_mov_b32_e32 v82, v80
	v_exp_f32_e32 v104, v104
	s_waitcnt lgkmcnt(12)
	v_mfma_f32_32x32x16_bf16 v[48:63], v[76:79], v[210:213], v[48:63]
	ds_read_b64_tr_b16 v[206:207], v172 offset:0x2600
	ds_read_b64_tr_b16 v[208:209], v172 offset:0x2e00
	v_exp_f32_e32 v105, v105
	v_exp_f32_e32 v106, v106
	v_mov_b32_e32 v83, v80
	v_exp_f32_e32 v107, v107
	s_waitcnt lgkmcnt(12)
	v_mfma_f32_32x32x16_bf16 v[32:47], v[64:67], v[182:185], v[32:47]
	ds_read_b64_tr_b16 v[210:211], v172 offset:0x3600
	ds_read_b64_tr_b16 v[212:213], v172 offset:0x3e00
	s_add_i32 s58, s52, 1
	s_and_b32 s58, s58, 3
	s_lshl_b32 s58, s58, 13
	v_add_u32_e32 v218, s58, v173
	ds_read_b128 v[182:185], v218 offset:49152
	v_exp_f32_e32 v108, v108
	v_exp_f32_e32 v109, v109
	v_mov_b32_e32 v84, v80
	v_exp_f32_e32 v110, v110
	s_waitcnt lgkmcnt(13)
	v_mfma_f32_32x32x16_bf16 v[32:47], v[68:71], v[186:189], v[32:47]
	ds_read_b128 v[186:189], v218 offset:53248
	v_exp_f32_e32 v111, v111
	v_exp_f32_e32 v236, v236
	v_mov_b32_e32 v85, v80
	v_exp_f32_e32 v237, v237
	s_waitcnt lgkmcnt(12)
	v_mfma_f32_32x32x16_bf16 v[32:47], v[72:75], v[190:193], v[32:47]
	v_add_u32_e32 v218, s58, v175
	ds_read_b128 v[190:193], v218 offset:49152
	v_exp_f32_e32 v238, v238
	v_exp_f32_e32 v239, v239
	v_mov_b32_e32 v86, v80
	v_exp_f32_e32 v240, v240
	s_waitcnt lgkmcnt(11)
	v_mfma_f32_32x32x16_bf16 v[32:47], v[76:79], v[194:197], v[32:47]
	ds_read_b128 v[194:197], v218 offset:53248
	v_exp_f32_e32 v241, v241
	v_exp_f32_e32 v242, v242
	v_mov_b32_e32 v87, v80
	v_exp_f32_e32 v243, v243
	s_waitcnt lgkmcnt(10)
	v_mfma_f32_32x32x16_bf16 v[16:31], v[64:67], v[198:201], v[16:31]
	v_add_u32_e32 v218, s58, v174
	ds_read_b128 v[198:201], v218 offset:49152
	v_exp_f32_e32 v244, v244
	v_mov_b32_e32 v88, v80
	v_exp_f32_e32 v245, v245
	v_mov_b32_e32 v89, v80
	s_waitcnt lgkmcnt(9)
	v_mfma_f32_32x32x16_bf16 v[16:31], v[68:71], v[202:205], v[16:31]
	ds_read_b128 v[202:205], v218 offset:53248
	v_exp_f32_e32 v246, v246
	v_mov_b32_e32 v90, v80
	v_exp_f32_e32 v247, v247
	v_mov_b32_e32 v91, v80
	s_waitcnt lgkmcnt(8)
	v_mfma_f32_32x32x16_bf16 v[16:31], v[72:75], v[206:209], v[16:31]
	v_add_u32_e32 v218, s58, v176
	ds_read_b128 v[206:209], v218 offset:49152
	v_exp_f32_e32 v248, v248
	v_mov_b32_e32 v92, v80
	v_exp_f32_e32 v249, v249
	v_mov_b32_e32 v93, v80
	s_waitcnt lgkmcnt(7)
	v_mfma_f32_32x32x16_bf16 v[16:31], v[76:79], v[210:213], v[16:31]
	ds_read_b128 v[210:213], v218 offset:53248
	v_exp_f32_e32 v250, v250
	v_mov_b32_e32 v94, v80
	v_exp_f32_e32 v251, v251
	v_mov_b32_e32 v95, v80
	s_cmp_lg_u32 s21, 0
	s_cbranch_scc1 .Lat_resc0
.Lat_rescback0:
	s_barrier
	s_mov_b32 s21, 0
	global_load_dwordx4 v[128:131], v233, s[24:25]
	global_load_dwordx4 v[132:135], v234, s[24:25]
	global_load_dwordx4 v[136:139], v232, s[24:25]
	s_add_u32 s24, s24, 0x10000
	s_addc_u32 s25, s25, 0
	v_add_f32_e32 v159, v96, v97
	v_cvt_pk_bf16_f32 v96, v96, v97
	v_add_f32_e32 v160, v98, v99
	v_cvt_pk_bf16_f32 v97, v98, v99
	v_add_f32_e32 v159, v100, v159
	s_waitcnt lgkmcnt(7)
	v_mfma_f32_32x32x16_bf16 v[64:79], v[182:185], v[124:127], v[80:95]
	v_add_f32_e32 v160, v101, v160
	v_cvt_pk_bf16_f32 v98, v100, v101
	v_add_f32_e32 v159, v102, v159
	v_add_f32_e32 v160, v103, v160
	v_cvt_pk_bf16_f32 v99, v102, v103
	v_add_f32_e32 v159, v104, v159
	s_waitcnt lgkmcnt(6)
	v_mfma_f32_32x32x16_bf16 v[80:95], v[186:189], v[124:127], v[80:95]
	s_lshl_b32 s79, s2, 14
	s_add_i32 s20, s52, 3
	s_and_b32 s20, s20, 3
	s_lshl_b32 s20, s20, 13
	s_waitcnt vmcnt(3)
	v_add_u32_e32 v217, s79, v168
	ds_write_b128 v217, v[140:143]
	v_add_u32_e32 v218, s79, v169
	ds_write_b128 v218, v[144:147]
	v_add_u32_e32 v217, s20, v170
	ds_write_b128 v217, v[148:151] offset:49152
	v_add_f32_e32 v160, v105, v160
	v_cvt_pk_bf16_f32 v100, v104, v105
	v_add_f32_e32 v159, v106, v159
	v_add_f32_e32 v160, v107, v160
	v_cvt_pk_bf16_f32 v101, v106, v107
	s_waitcnt lgkmcnt(8)
	v_mfma_f32_32x32x16_bf16 v[64:79], v[190:193], v[120:123], v[64:79]
	v_add_f32_e32 v159, v108, v159
	v_add_f32_e32 v160, v109, v160
	v_cvt_pk_bf16_f32 v102, v108, v109
	v_add_f32_e32 v159, v110, v159
	v_add_f32_e32 v160, v111, v160
	v_cvt_pk_bf16_f32 v103, v110, v111
	s_waitcnt lgkmcnt(7)
	v_mfma_f32_32x32x16_bf16 v[80:95], v[194:197], v[120:123], v[80:95]
	s_lshl_b32 s59, s1, 14
	v_add_u32_e32 v172, s59, v177
	ds_read_b64_tr_b16 v[182:183], v172 offset:0x0
	ds_read_b64_tr_b16 v[184:185], v172 offset:0x800
	ds_read_b64_tr_b16 v[186:187], v172 offset:0x1000
	ds_read_b64_tr_b16 v[188:189], v172 offset:0x1800
	ds_read_b64_tr_b16 v[190:191], v172 offset:0x2000
	ds_read_b64_tr_b16 v[192:193], v172 offset:0x2800
	ds_read_b64_tr_b16 v[194:195], v172 offset:0x3000
	ds_read_b64_tr_b16 v[196:197], v172 offset:0x3800
	v_add_f32_e32 v159, v236, v159
	v_add_f32_e32 v160, v237, v160
	v_cvt_pk_bf16_f32 v104, v236, v237
	v_add_f32_e32 v159, v238, v159
	v_add_f32_e32 v160, v239, v160
	v_cvt_pk_bf16_f32 v105, v238, v239
	s_waitcnt lgkmcnt(14)
; #define SBAR() __builtin_amdgcn_sched_barrier(0)
; #define SLOAD(i, k0) do { sr_[i].vs0 = *reinterpret_cast<const bf16x8*>(&Vh[(long)((k0) + sr) * LDQ + sc]); sr_[i].vs1 = *reinterpret_cast<const bf16x8*>(&Vh[(long)((k0) + 32 + sr) * LDQ + sc]); \
;     sr_[i].ks0 = *reinterpret_cast<const bf16x8*>(&Kh[(long)((k0) + kr) * LDQ + kc]); } while (0)
; #define SWRITE(b, i) do { *(bf16x8*)(V_lds + (b) * SHM_V + vst0) = sr_[i].vs0; *(bf16x8*)(V_lds + (b) * SHM_V + vst1) = sr_[i].vs1; \
;     *(bf16x8*)(K_lds + (b) * SHM_K + kst) = sr_[i].ks0; } while (0)
; template <int D0> __device__ __forceinline__ void pv_one(f32x16& od, int vb, bf16x8 pa0, bf16x8 pa1, bf16x8 pa2, bf16x8 pa3) {
;   const s16x4 l0 = tr_read<v_rd_off(D0, 0, 0)>(vb), h0 = tr_read<v_rd_off(D0, 0, 1)>(vb), l1 = tr_read<v_rd_off(D0, 1, 0)>(vb), h1 = tr_read<v_rd_off(D0, 1, 1)>(vb);
;   const s16x4 l2 = tr_read<v_rd_off(D0, 2, 0)>(vb), h2 = tr_read<v_rd_off(D0, 2, 1)>(vb), l3 = tr_read<v_rd_off(D0, 3, 0)>(vb), h3 = tr_read<v_rd_off(D0, 3, 1)>(vb);
;   asm volatile("s_waitcnt lgkmcnt(0)" ::: "memory"); SBAR();
;     ...
;   od = __builtin_amdgcn_mfma_f32_32x32x16_bf16(pa0, PK(l0, h0), od, 0, 0, 0);
;   od = __builtin_amdgcn_mfma_f32_32x32x16_bf16(pa1, PK(l1, h1), od, 0, 0, 0);
;   od = __builtin_amdgcn_mfma_f32_32x32x16_bf16(pa2, PK(l2, h2), od, 0, 0, 0);
;   od = __builtin_amdgcn_mfma_f32_32x32x16_bf16(pa3, PK(l3, h3), od, 0, 0, 0);
;     ...
; }
; __device__ __forceinline__ void pv_d0(f32x16* o, int vb, bf16x8 pa0, bf16x8 pa1, bf16x8 pa2, bf16x8 pa3) {
;   pv_one<0>(o[0], vb, pa0, pa1, pa2, pa3); pv_one<1>(o[1], vb, pa0, pa1, pa2, pa3); pv_one<2>(o[2], vb, pa0, pa1, pa2, pa3); pv_one<3>(o[3], vb, pa0, pa1, pa2, pa3);
; __device__ __forceinline__ void attn_unit(const bf16_t* __restrict__ Qb, const bf16_t* __restrict__ Kh, const bf16_t* __restrict__ Vh, int seq, char* lds,
;                                           int mode, float* scratch, float lam, float gscale, const float* __restrict__ subg, bf16_t* outp) {
;     ...
;     SBAR(); qkt(pA0, pA1, K_lds + bc * SHM_K, qr, r32, hi, m_reg);
;     finishSM(pB0, pB1, alB, l_reg, pa0, pa1, pa2, pa3); SBAR();
;     if (j + 3 < NT) SLOAD(SE, (j + 3) * KVBLK); SBAR();
;     pv_d0(o, vb0 + bp * SHM_V, pa0, pa1, pa2, pa3); partialSM(pA0, pA1, m_reg, alA, false);
;     SWAIT(); SWRITE(bn, SO);
;     RESC(alA); __syncthreads(); ROT3();
;   }
	v_mfma_f32_32x32x16_bf16 v[64:79], v[198:201], v[116:119], v[64:79]
	v_add_f32_e32 v159, v240, v159
	v_add_f32_e32 v160, v241, v160
	v_cvt_pk_bf16_f32 v106, v240, v241
	v_add_f32_e32 v159, v242, v159
	v_add_f32_e32 v160, v243, v160
	v_cvt_pk_bf16_f32 v107, v242, v243
	s_waitcnt lgkmcnt(13)
	v_mfma_f32_32x32x16_bf16 v[80:95], v[202:205], v[116:119], v[80:95]
	s_waitcnt lgkmcnt(8)
	ds_read_b64_tr_b16 v[198:199], v172 offset:0x200
	ds_read_b64_tr_b16 v[200:201], v172 offset:0xa00
	ds_read_b64_tr_b16 v[202:203], v172 offset:0x1200
	ds_read_b64_tr_b16 v[204:205], v172 offset:0x1a00
	v_add_f32_e32 v159, v244, v159
	v_add_f32_e32 v160, v245, v160
	v_cvt_pk_bf16_f32 v108, v244, v245
	v_add_f32_e32 v159, v246, v159
	v_add_f32_e32 v160, v247, v160
	v_cvt_pk_bf16_f32 v109, v246, v247
	v_add_f32_e32 v159, v248, v159
	v_mfma_f32_32x32x16_bf16 v[64:79], v[206:209], v[112:115], v[64:79]
	ds_read_b64_tr_b16 v[206:207], v172 offset:0x2200
	ds_read_b64_tr_b16 v[208:209], v172 offset:0x2a00
	v_add_f32_e32 v160, v249, v160
	v_cvt_pk_bf16_f32 v110, v248, v249
	v_add_f32_e32 v159, v250, v159
	v_add_f32_e32 v160, v251, v160
	v_cvt_pk_bf16_f32 v111, v250, v251
	v_add_f32_e32 v159, v159, v160
	v_fma_f32 v167, v167, v158, v159
	v_mfma_f32_32x32x16_bf16 v[80:95], v[210:213], v[112:115], v[80:95]
	s_waitcnt lgkmcnt(12)
	v_mfma_f32_32x32x16_bf16 v[0:15], v[96:99], v[182:185], v[0:15]
	ds_read_b64_tr_b16 v[210:211], v172 offset:0x3200
	ds_read_b64_tr_b16 v[212:213], v172 offset:0x3a00
	v_max3_f32 v161, v64, v65, v66
	v_max3_f32 v161, v161, v67, v68
	v_max3_f32 v161, v161, v69, v70
	v_max3_f32 v161, v161, v71, v72
	s_waitcnt lgkmcnt(12)
	v_mfma_f32_32x32x16_bf16 v[0:15], v[100:103], v[186:189], v[0:15]
	ds_read_b64_tr_b16 v[182:183], v172 offset:0x400
	ds_read_b64_tr_b16 v[184:185], v172 offset:0xc00
	v_max3_f32 v161, v161, v73, v74
	v_max3_f32 v161, v161, v75, v76
	v_max3_f32 v161, v161, v77, v78
	v_max_f32_e32 v161, v161, v79
	s_waitcnt lgkmcnt(12)
	v_mfma_f32_32x32x16_bf16 v[0:15], v[104:107], v[190:193], v[0:15]
	ds_read_b64_tr_b16 v[186:187], v172 offset:0x1400
	ds_read_b64_tr_b16 v[188:189], v172 offset:0x1c00
	v_max3_f32 v216, v80, v81, v82
	v_max3_f32 v216, v216, v83, v84
	v_max3_f32 v216, v216, v85, v86
	v_max3_f32 v216, v216, v87, v88
	s_waitcnt lgkmcnt(12)
	v_mfma_f32_32x32x16_bf16 v[0:15], v[108:111], v[194:197], v[0:15]
	ds_read_b64_tr_b16 v[190:191], v172 offset:0x2400
	ds_read_b64_tr_b16 v[192:193], v172 offset:0x2c00
	v_max3_f32 v216, v216, v89, v90
	v_max3_f32 v216, v216, v91, v92
	v_max3_f32 v216, v216, v93, v94
	v_max_f32_e32 v216, v216, v95
	v_max_f32_e32 v161, v161, v216
	v_cmp_ge_f32_e32 vcc, s66, v161
	s_cmp_eq_u64 vcc, exec
	s_cbranch_scc0 .Lat_rare1
	v_mov_b32_e32 v235, 1.0
.Lat_back1:
	s_waitcnt lgkmcnt(12)
	v_mfma_f32_32x32x16_bf16 v[48:63], v[96:99], v[198:201], v[48:63]
	ds_read_b64_tr_b16 v[194:195], v172 offset:0x3400
	ds_read_b64_tr_b16 v[196:197], v172 offset:0x3c00
	v_exp_f32_e32 v64, v64
	v_exp_f32_e32 v65, v65
	v_xor_b32_e32 v236, 0x80000000, v181
	v_exp_f32_e32 v66, v66
	s_waitcnt lgkmcnt(12)
	v_mfma_f32_32x32x16_bf16 v[48:63], v[100:103], v[202:205], v[48:63]
	ds_read_b64_tr_b16 v[198:199], v172 offset:0x600
	ds_read_b64_tr_b16 v[200:201], v172 offset:0xe00
	v_exp_f32_e32 v67, v67
	v_exp_f32_e32 v68, v68
	v_mov_b32_e32 v237, v236
	v_exp_f32_e32 v69, v69
	s_waitcnt lgkmcnt(12)
	v_mfma_f32_32x32x16_bf16 v[48:63], v[104:107], v[206:209], v[48:63]
	ds_read_b64_tr_b16 v[202:203], v172 offset:0x1600
	ds_read_b64_tr_b16 v[204:205], v172 offset:0x1e00
	v_exp_f32_e32 v70, v70
	v_exp_f32_e32 v71, v71
	v_mov_b32_e32 v238, v236
	v_exp_f32_e32 v72, v72
	s_waitcnt lgkmcnt(12)
	v_mfma_f32_32x32x16_bf16 v[48:63], v[108:111], v[210:213], v[48:63]
	ds_read_b64_tr_b16 v[206:207], v172 offset:0x2600
	ds_read_b64_tr_b16 v[208:209], v172 offset:0x2e00
	v_exp_f32_e32 v73, v73
	v_exp_f32_e32 v74, v74
	v_mov_b32_e32 v239, v236
	v_exp_f32_e32 v75, v75
	s_waitcnt lgkmcnt(12)
	v_mfma_f32_32x32x16_bf16 v[32:47], v[96:99], v[182:185], v[32:47]
	ds_read_b64_tr_b16 v[210:211], v172 offset:0x3600
	ds_read_b64_tr_b16 v[212:213], v172 offset:0x3e00
	s_add_i32 s58, s52, 2
	s_and_b32 s58, s58, 3
	s_lshl_b32 s58, s58, 13
	v_add_u32_e32 v218, s58, v173
	ds_read_b128 v[182:185], v218 offset:49152
	v_exp_f32_e32 v76, v76
	v_exp_f32_e32 v77, v77
	v_mov_b32_e32 v240, v236
	v_exp_f32_e32 v78, v78
	s_waitcnt lgkmcnt(13)
	v_mfma_f32_32x32x16_bf16 v[32:47], v[100:103], v[186:189], v[32:47]
	ds_read_b128 v[186:189], v218 offset:53248
	v_exp_f32_e32 v79, v79
	v_exp_f32_e32 v80, v80
	v_mov_b32_e32 v241, v236
	v_exp_f32_e32 v81, v81
	s_waitcnt lgkmcnt(12)
	v_mfma_f32_32x32x16_bf16 v[32:47], v[104:107], v[190:193], v[32:47]
	v_add_u32_e32 v218, s58, v175
	ds_read_b128 v[190:193], v218 offset:49152
	v_exp_f32_e32 v82, v82
	v_exp_f32_e32 v83, v83
	v_mov_b32_e32 v242, v236
	v_exp_f32_e32 v84, v84
	s_waitcnt lgkmcnt(11)
	v_mfma_f32_32x32x16_bf16 v[32:47], v[108:111], v[194:197], v[32:47]
	ds_read_b128 v[194:197], v218 offset:53248
	v_exp_f32_e32 v85, v85
	v_exp_f32_e32 v86, v86
	v_mov_b32_e32 v243, v236
	v_exp_f32_e32 v87, v87
	s_waitcnt lgkmcnt(10)
	v_mfma_f32_32x32x16_bf16 v[16:31], v[96:99], v[198:201], v[16:31]
	v_add_u32_e32 v218, s58, v174
	ds_read_b128 v[198:201], v218 offset:49152
	v_exp_f32_e32 v88, v88
	v_mov_b32_e32 v244, v236
	v_exp_f32_e32 v89, v89
	v_mov_b32_e32 v245, v236
	s_waitcnt lgkmcnt(9)
	v_mfma_f32_32x32x16_bf16 v[16:31], v[100:103], v[202:205], v[16:31]
	ds_read_b128 v[202:205], v218 offset:53248
	v_exp_f32_e32 v90, v90
	v_mov_b32_e32 v246, v236
	v_exp_f32_e32 v91, v91
	v_mov_b32_e32 v247, v236
	s_waitcnt lgkmcnt(8)
	v_mfma_f32_32x32x16_bf16 v[16:31], v[104:107], v[206:209], v[16:31]
	v_add_u32_e32 v218, s58, v176
	ds_read_b128 v[206:209], v218 offset:49152
	v_exp_f32_e32 v92, v92
	v_mov_b32_e32 v248, v236
	v_exp_f32_e32 v93, v93
	v_mov_b32_e32 v249, v236
	s_waitcnt lgkmcnt(7)
	v_mfma_f32_32x32x16_bf16 v[16:31], v[108:111], v[210:213], v[16:31]
	ds_read_b128 v[210:213], v218 offset:53248
	v_exp_f32_e32 v94, v94
	v_mov_b32_e32 v250, v236
	v_exp_f32_e32 v95, v95
	v_mov_b32_e32 v251, v236
	s_cmp_lg_u32 s21, 0
	s_cbranch_scc1 .Lat_resc1
.Lat_rescback1:
	s_add_i32 s52, s52, 2
	s_cmpk_gt_u32 s52, 0xfe
	s_barrier
	s_cbranch_scc1 .Lat_exit
	s_mov_b32 s58, s2
	s_mov_b32 s2, s0
	s_mov_b32 s0, s1
	s_mov_b32 s1, s58
	s_branch .Lat_loop

; #define SBAR() __builtin_amdgcn_sched_barrier(0)
; #define RESC(a) do { if (__any((a) < 1.f)) { if (hi == 0) al_l[r32] = (a); asm volatile("s_waitcnt lgkmcnt(0)" ::: "memory"); \
;     _Pragma("unroll") for (int d = 0; d < 4; ++d) _Pragma("unroll") for (int r = 0; r < 16; ++r) o[d][r] *= al_l[crow(r, hi)]; } } while (0)
; #define ROT3() do { const int t_ = bp; bp = bc; bc = bn; bn = t_; } while (0)
; __device__ __forceinline__ void attn_unit(const bf16_t* __restrict__ Qb, const bf16_t* __restrict__ Kh, const bf16_t* __restrict__ Vh, int seq, char* lds,
;                                           int mode, float* scratch, float lam, float gscale, const float* __restrict__ subg, bf16_t* outp) {
;     ...
;     RESC(alA); __syncthreads(); ROT3();
;   }
;   SBAR(); qkt(pB0, pB1, K_lds + bc * SHM_K, qr, r32, hi, m_reg);
;   finishSM(pA0, pA1, alA, l_reg, pa0, pa1, pa2, pa3); SBAR();
.Lat_resc0:
	s_and_saveexec_b64 s[58:59], s[4:5]
	ds_write_b32 v153, v158 offset:128
	s_or_b64 exec, exec, s[58:59]
	s_waitcnt lgkmcnt(0)
	v_add_u32_e32 v217, v166, v178
	ds_read_b128 v[128:131], v217 offset:224
	ds_read_b128 v[132:135], v217 offset:192
	s_waitcnt lgkmcnt(0)
	v_pk_mul_f32 v[12:13], v[12:13], v[128:129]
	v_pk_mul_f32 v[14:15], v[14:15], v[130:131]
	v_pk_mul_f32 v[8:9], v[8:9], v[132:133]
	v_pk_mul_f32 v[10:11], v[10:11], v[134:135]
	v_pk_mul_f32 v[60:61], v[60:61], v[128:129]
	v_pk_mul_f32 v[62:63], v[62:63], v[130:131]
	v_pk_mul_f32 v[56:57], v[56:57], v[132:133]
	v_pk_mul_f32 v[58:59], v[58:59], v[134:135]
	v_pk_mul_f32 v[44:45], v[44:45], v[128:129]
	v_pk_mul_f32 v[46:47], v[46:47], v[130:131]
	v_pk_mul_f32 v[40:41], v[40:41], v[132:133]
	v_pk_mul_f32 v[42:43], v[42:43], v[134:135]
	v_pk_mul_f32 v[28:29], v[28:29], v[128:129]
	v_pk_mul_f32 v[30:31], v[30:31], v[130:131]
	v_pk_mul_f32 v[24:25], v[24:25], v[132:133]
	v_pk_mul_f32 v[26:27], v[26:27], v[134:135]
	ds_read_b128 v[128:131], v217 offset:160
	ds_read_b128 v[132:135], v217 offset:128
	s_waitcnt lgkmcnt(0)
	v_pk_mul_f32 v[4:5], v[4:5], v[128:129]
	v_pk_mul_f32 v[6:7], v[6:7], v[130:131]
	v_pk_mul_f32 v[0:1], v[0:1], v[132:133]
	v_pk_mul_f32 v[2:3], v[2:3], v[134:135]
	v_pk_mul_f32 v[52:53], v[52:53], v[128:129]
	v_pk_mul_f32 v[54:55], v[54:55], v[130:131]
	v_pk_mul_f32 v[48:49], v[48:49], v[132:133]
	v_pk_mul_f32 v[50:51], v[50:51], v[134:135]
	v_pk_mul_f32 v[36:37], v[36:37], v[128:129]
	v_pk_mul_f32 v[38:39], v[38:39], v[130:131]
	v_pk_mul_f32 v[32:33], v[32:33], v[132:133]
	v_pk_mul_f32 v[34:35], v[34:35], v[134:135]
	v_pk_mul_f32 v[20:21], v[20:21], v[128:129]
	v_pk_mul_f32 v[22:23], v[22:23], v[130:131]
	v_pk_mul_f32 v[16:17], v[16:17], v[132:133]
	v_pk_mul_f32 v[18:19], v[18:19], v[134:135]
	s_branch .Lat_rescback0
.Lat_resc1:
	s_and_saveexec_b64 s[58:59], s[4:5]
	ds_write_b32 v153, v235 offset:128
	s_or_b64 exec, exec, s[58:59]
	s_waitcnt lgkmcnt(0)
	v_add_u32_e32 v217, v166, v178
	ds_read_b128 v[140:143], v217 offset:224
	ds_read_b128 v[144:147], v217 offset:192
	s_waitcnt lgkmcnt(0)
	v_pk_mul_f32 v[12:13], v[12:13], v[140:141]
	v_pk_mul_f32 v[14:15], v[14:15], v[142:143]
	v_pk_mul_f32 v[8:9], v[8:9], v[144:145]
	v_pk_mul_f32 v[10:11], v[10:11], v[146:147]
	v_pk_mul_f32 v[60:61], v[60:61], v[140:141]
	v_pk_mul_f32 v[62:63], v[62:63], v[142:143]
	v_pk_mul_f32 v[56:57], v[56:57], v[144:145]
	v_pk_mul_f32 v[58:59], v[58:59], v[146:147]
	v_pk_mul_f32 v[44:45], v[44:45], v[140:141]
	v_pk_mul_f32 v[46:47], v[46:47], v[142:143]
	v_pk_mul_f32 v[40:41], v[40:41], v[144:145]
	v_pk_mul_f32 v[42:43], v[42:43], v[146:147]
	v_pk_mul_f32 v[28:29], v[28:29], v[140:141]
	v_pk_mul_f32 v[30:31], v[30:31], v[142:143]
	v_pk_mul_f32 v[24:25], v[24:25], v[144:145]
	v_pk_mul_f32 v[26:27], v[26:27], v[146:147]
	ds_read_b128 v[140:143], v217 offset:160
	ds_read_b128 v[144:147], v217 offset:128
	s_waitcnt lgkmcnt(0)
	v_pk_mul_f32 v[4:5], v[4:5], v[140:141]
	v_pk_mul_f32 v[6:7], v[6:7], v[142:143]
	v_pk_mul_f32 v[0:1], v[0:1], v[144:145]
	v_pk_mul_f32 v[2:3], v[2:3], v[146:147]
	v_pk_mul_f32 v[52:53], v[52:53], v[140:141]
	v_pk_mul_f32 v[54:55], v[54:55], v[142:143]
	v_pk_mul_f32 v[48:49], v[48:49], v[144:145]
	v_pk_mul_f32 v[50:51], v[50:51], v[146:147]
	v_pk_mul_f32 v[36:37], v[36:37], v[140:141]
	v_pk_mul_f32 v[38:39], v[38:39], v[142:143]
	v_pk_mul_f32 v[32:33], v[32:33], v[144:145]
	v_pk_mul_f32 v[34:35], v[34:35], v[146:147]
	v_pk_mul_f32 v[20:21], v[20:21], v[140:141]
	v_pk_mul_f32 v[22:23], v[22:23], v[142:143]
	v_pk_mul_f32 v[16:17], v[16:17], v[144:145]
	v_pk_mul_f32 v[18:19], v[18:19], v[146:147]
	s_branch .Lat_rescback1
.Lat_exit:
	s_waitcnt vmcnt(0) lgkmcnt(0)
	v_mov_b32_e32 v160, v64
	v_mov_b32_e32 v192, v65
	v_mov_b32_e32 v151, v66
	v_mov_b32_e32 v161, v67
	v_mov_b32_e32 v149, v68
	v_mov_b32_e32 v159, v69
	v_mov_b32_e32 v148, v70
	v_mov_b32_e32 v150, v71
	v_mov_b32_e32 v145, v72
	v_mov_b32_e32 v147, v73
	v_mov_b32_e32 v143, v74
	v_mov_b32_e32 v146, v75
	v_mov_b32_e32 v141, v76
	v_mov_b32_e32 v144, v77
	v_mov_b32_e32 v140, v78
	v_mov_b32_e32 v142, v79
	v_mov_b32_e32 v64, v80
	v_mov_b32_e32 v65, v81
	v_mov_b32_e32 v66, v82
	v_mov_b32_e32 v67, v83
	v_mov_b32_e32 v68, v84
	v_mov_b32_e32 v69, v85
	v_mov_b32_e32 v70, v86
	v_mov_b32_e32 v71, v87
	v_mov_b32_e32 v72, v88
	v_mov_b32_e32 v73, v89
	v_mov_b32_e32 v74, v90
	v_mov_b32_e32 v75, v91
	v_mov_b32_e32 v76, v92
	v_mov_b32_e32 v77, v93
	v_mov_b32_e32 v78, v94
	v_mov_b32_e32 v79, v95
	v_mov_b32_e32 v158, v235
	v_mov_b32_e32 v216, v167
	s_mov_b32 s1, s2
	s_lshl_b32 s59, s0, 14
	v_permlane32_swap_b32_e32 v167, v216
	v_add_f32_e32 v167, v167, v216
	s_lshl_b32 s2, s1, 14
	v_add_u32_e32 v172, s2, v177
	s_and_b32 s2, s52, 3
	s_lshl_b32 s2, s2, 13
	s_mov_b32 s79, 0
; #define SBAR() __builtin_amdgcn_sched_barrier(0)
; __device__ __forceinline__ void finishSM(f32x16& p0, f32x16& p1, float alpha, float& l_reg, bf16x8& pa0, bf16x8& pa1, bf16x8& pa2, bf16x8& pa3) {
; #pragma unroll
;   for (int r = 0; r < 16; ++r) p1[r] = __builtin_amdgcn_exp2f(p1[r]);
;   float ps = 0;
; #pragma unroll
;   for (int r = 0; r < 16; ++r) ps += p0[r];
; #pragma unroll
;   for (int r = 0; r < 16; ++r) ps += p1[r];
;   { auto rr = __builtin_amdgcn_permlane32_swap(__float_as_uint(ps), __float_as_uint(ps), false, false);
;     ps = __uint_as_float(rr[0]) + __uint_as_float(rr[1]); }
;   l_reg = l_reg * alpha + ps;
;     ...
;   PK4(p0, 0, pa0); PK4(p0, 8, pa1); PK4(p1, 0, pa2); PK4(p1, 8, pa3);
;     ...
; }
; __device__ __forceinline__ void qkt(f32x16& p0, f32x16& p1, const char* Ks, const bf16x8* qr, int r32, int hi, float m_ref) {
; #pragma unroll
;   for (int r = 0; r < 16; ++r) { p0[r] = -m_ref; p1[r] = -m_ref; }
; #pragma unroll
;   for (int d0 = 0; d0 < 4; ++d0) { const int cb = (d0 * 16 + hi * 8) * 2;
;     bf16x8 b0 = *reinterpret_cast<const bf16x8*>(Ks + KSWZ(r32, cb));
;     bf16x8 b1 = *reinterpret_cast<const bf16x8*>(Ks + KSWZ(32 + r32, cb));
;     p0 = __builtin_amdgcn_mfma_f32_32x32x16_bf16(b0, qr[d0], p0, 0, 0, 0);
;     p1 = __builtin_amdgcn_mfma_f32_32x32x16_bf16(b1, qr[d0], p1, 0, 0, 0); }
; }
; __device__ __forceinline__ void attn_unit(const bf16_t* __restrict__ Qb, const bf16_t* __restrict__ Kh, const bf16_t* __restrict__ Vh, int seq, char* lds,
;                                           int mode, float* scratch, float lam, float gscale, const float* __restrict__ subg, bf16_t* outp) {
;     ...
;   SBAR(); qkt(pB0, pB1, K_lds + bc * SHM_K, qr, r32, hi, m_reg);
;   finishSM(pA0, pA1, alA, l_reg, pa0, pa1, pa2, pa3); SBAR();
;   pv_d0(o, vb0 + bp * SHM_V, pa0, pa1, pa2, pa3); partialSM(pB0, pB1, m_reg, alB, false);
.LBB0_1349:
	s_sub_i32 s0, s2, s79
	v_add_u32_e32 v132, s0, v173
	ds_read_b128 v[128:131], v132 offset:49152
	v_xor_b32_e32 v80, 0x80000000, v181
	v_mov_b32_e32 v81, v80
	v_mov_b32_e32 v82, v80
	v_mov_b32_e32 v83, v80
	v_mov_b32_e32 v84, v80
	v_mov_b32_e32 v85, v80
	v_mov_b32_e32 v86, v80
	v_mov_b32_e32 v87, v80
	v_mov_b32_e32 v88, v80
	v_mov_b32_e32 v89, v80
	v_mov_b32_e32 v90, v80
	v_mov_b32_e32 v91, v80
	v_mov_b32_e32 v92, v80
	v_mov_b32_e32 v93, v80
	v_mov_b32_e32 v94, v80
	v_mov_b32_e32 v95, v80
	v_add_u32_e32 v136, s0, v176
	v_mov_b32_e32 v137, v65
	s_waitcnt lgkmcnt(0)
	v_mfma_f32_32x32x16_bf16 v[96:111], v[128:131], v[124:127], v[80:95]
	ds_read_b128 v[128:131], v132 offset:53248
	v_add_u32_e32 v132, s0, v174
	v_mov_b32_e32 v138, v66
	v_mov_b32_e32 v139, v67
	v_mov_b32_e32 v154, v68
	v_mov_b32_e32 v155, v73
	v_mov_b32_e32 v156, v74
	s_waitcnt lgkmcnt(0)
	v_mfma_f32_32x32x16_bf16 v[80:95], v[128:131], v[124:127], v[80:95]
	v_add_u32_e32 v128, s0, v175
	ds_read_b128 v[124:127], v128 offset:49152
	v_mov_b32_e32 v157, v75
	v_mov_b32_e32 v78, v78
	v_mov_b32_e32 v79, v79
	s_waitcnt lgkmcnt(0)
	v_mfma_f32_32x32x16_bf16 v[96:111], v[124:127], v[120:123], v[96:111]
	ds_read_b128 v[124:127], v128 offset:53248
	ds_read_b128 v[128:131], v132 offset:49152
	ds_read_b128 v[132:135], v132 offset:53248
	s_waitcnt lgkmcnt(2)
	v_mfma_f32_32x32x16_bf16 v[80:95], v[124:127], v[120:123], v[80:95]
	ds_read_b128 v[120:123], v136 offset:49152
	ds_read_b128 v[124:127], v136 offset:53248
	v_mov_b32_e32 v136, v64
	v_add_f32_e32 v64, 0, v160
	v_add_f32_e32 v64, v192, v64
	v_add_f32_e32 v64, v151, v64
	v_add_f32_e32 v64, v161, v64
	v_add_f32_e32 v64, v149, v64
	v_add_f32_e32 v64, v159, v64
	v_add_f32_e32 v64, v148, v64
	v_add_f32_e32 v64, v150, v64
	v_add_f32_e32 v64, v145, v64
	v_add_f32_e32 v64, v147, v64
	v_add_f32_e32 v64, v143, v64
	v_add_f32_e32 v64, v146, v64
	v_add_f32_e32 v64, v141, v64
	v_add_f32_e32 v64, v144, v64
	v_add_f32_e32 v64, v140, v64
	v_add_f32_e32 v64, v142, v64
	v_add_f32_e32 v64, v136, v64
	s_waitcnt lgkmcnt(3)
	v_mfma_f32_32x32x16_bf16 v[96:111], v[128:131], v[116:119], v[96:111]
	v_mov_b32_e32 v128, v69
	v_add_f32_e32 v64, v137, v64
	v_mov_b32_e32 v129, v70
	v_add_f32_e32 v64, v138, v64
	v_mov_b32_e32 v130, v71
	v_add_f32_e32 v64, v139, v64
	v_mov_b32_e32 v131, v72
	s_waitcnt lgkmcnt(2)
	v_mfma_f32_32x32x16_bf16 v[80:95], v[132:135], v[116:119], v[80:95]
	v_add_f32_e32 v64, v154, v64
	v_add_f32_e32 v64, v128, v64
	v_add_f32_e32 v64, v129, v64
	v_add_f32_e32 v64, v130, v64
	v_mov_b32_e32 v116, v76
	v_add_f32_e32 v64, v131, v64
	v_mov_b32_e32 v117, v77
	v_add_f32_e32 v64, v155, v64
	s_waitcnt lgkmcnt(1)
	v_mfma_f32_32x32x16_bf16 v[96:111], v[120:123], v[112:115], v[96:111]
	v_add_f32_e32 v64, v156, v64
	v_add_f32_e32 v64, v157, v64
	v_add_f32_e32 v64, v116, v64
	v_add_f32_e32 v64, v117, v64
	v_add_f32_e32 v64, v78, v64
	v_add_f32_e32 v64, v79, v64
	v_mov_b32_e32 v65, v64
	s_waitcnt lgkmcnt(0)
	v_mfma_f32_32x32x16_bf16 v[80:95], v[124:127], v[112:115], v[80:95]
	v_cvt_pk_bf16_f32 v66, v160, v192
	v_cvt_pk_bf16_f32 v67, v151, v161
	v_cvt_pk_bf16_f32 v68, v149, v159
	v_cvt_pk_bf16_f32 v69, v148, v150
	v_permlane32_swap_b32_e32 v64, v65
	s_nop 0
	s_nop 0
	v_cvt_pk_bf16_f32 v70, v145, v147
	v_cvt_pk_bf16_f32 v71, v143, v146
	v_cvt_pk_bf16_f32 v72, v141, v144
	v_cvt_pk_bf16_f32 v73, v140, v142
	v_cvt_pk_bf16_f32 v74, v136, v137
	v_cvt_pk_bf16_f32 v75, v138, v139
	v_cvt_pk_bf16_f32 v76, v154, v128
	v_cvt_pk_bf16_f32 v77, v129, v130
	v_cvt_pk_bf16_f32 v112, v131, v155
	v_cvt_pk_bf16_f32 v113, v156, v157
	v_cvt_pk_bf16_f32 v114, v116, v117
	v_cvt_pk_bf16_f32 v115, v78, v79
	s_nop 0
	s_nop 0
	s_nop 0
	s_nop 0
	s_nop 0
	s_nop 0
	s_nop 0
	v_add_u32_e32 v78, s59, v177
	ds_read_b64_tr_b16 v[116:117], v78 offset:0
	ds_read_b64_tr_b16 v[118:119], v78 offset:0x800
	ds_read_b64_tr_b16 v[120:121], v78 offset:0x1000
	ds_read_b64_tr_b16 v[122:123], v78 offset:0x1800
	ds_read_b64_tr_b16 v[124:125], v78 offset:0x2000
	ds_read_b64_tr_b16 v[126:127], v78 offset:0x2800
	ds_read_b64_tr_b16 v[128:129], v78 offset:0x3000
	ds_read_b64_tr_b16 v[130:131], v78 offset:0x3800
	s_waitcnt lgkmcnt(0)
; #define RESC(a) do { if (__any((a) < 1.f)) { if (hi == 0) al_l[r32] = (a); asm volatile("s_waitcnt lgkmcnt(0)" ::: "memory"); \
;     _Pragma("unroll") for (int d = 0; d < 4; ++d) _Pragma("unroll") for (int r = 0; r < 16; ++r) o[d][r] *= al_l[crow(r, hi)]; } } while (0)
; __device__ __forceinline__ void partialSM(f32x16& p0, f32x16& p1, float& m_ref, float& alpha, bool first) {
;   constexpr float THRL = THR * 1.4426950408889634f;
;   float pmax = p0[0];
; #pragma unroll
;   for (int r = 1; r < 16; ++r) pmax = fmaxf(pmax, p0[r]);
; #pragma unroll
;   for (int r = 0; r < 16; ++r) pmax = fmaxf(pmax, p1[r]);
;   { auto rr = __builtin_amdgcn_permlane32_swap(__float_as_uint(pmax), __float_as_uint(pmax), false, false);
;     pmax = fmaxf(__uint_as_float(rr[0]), __uint_as_float(rr[1])); }
;   if (__builtin_expect(!first && __all(pmax <= THRL), 1)) { alpha = 1.f; }
; __device__ __forceinline__ void attn_unit(const bf16_t* __restrict__ Qb, const bf16_t* __restrict__ Kh, const bf16_t* __restrict__ Vh, int seq, char* lds,
;                                           int mode, float* scratch, float lam, float gscale, const float* __restrict__ subg, bf16_t* outp) {
;     ...
;   pv_d0(o, vb0 + bp * SHM_V, pa0, pa1, pa2, pa3); partialSM(pB0, pB1, m_reg, alB, false);
;   RESC(alB);
	s_nop 0
	v_mfma_f32_32x32x16_bf16 v[0:15], v[66:69], v[116:119], v[0:15]
	ds_read_b64_tr_b16 v[116:117], v78 offset:0x200
	ds_read_b64_tr_b16 v[118:119], v78 offset:0xa00
	v_mfma_f32_32x32x16_bf16 v[0:15], v[70:73], v[120:123], v[0:15]
	ds_read_b64_tr_b16 v[120:121], v78 offset:0x1200
	ds_read_b64_tr_b16 v[122:123], v78 offset:0x1a00
	v_mfma_f32_32x32x16_bf16 v[0:15], v[74:77], v[124:127], v[0:15]
	ds_read_b64_tr_b16 v[124:125], v78 offset:0x2200
	ds_read_b64_tr_b16 v[126:127], v78 offset:0x2a00
	v_mfma_f32_32x32x16_bf16 v[0:15], v[112:115], v[128:131], v[0:15]
	ds_read_b64_tr_b16 v[128:129], v78 offset:0x3200
	ds_read_b64_tr_b16 v[130:131], v78 offset:0x3a00
	s_waitcnt lgkmcnt(0)
	v_mfma_f32_32x32x16_bf16 v[48:63], v[66:69], v[116:119], v[48:63]
	ds_read_b64_tr_b16 v[116:117], v78 offset:0x400
	ds_read_b64_tr_b16 v[118:119], v78 offset:0xc00
	v_mfma_f32_32x32x16_bf16 v[48:63], v[70:73], v[120:123], v[48:63]
	ds_read_b64_tr_b16 v[120:121], v78 offset:0x1400
	ds_read_b64_tr_b16 v[122:123], v78 offset:0x1c00
	v_mfma_f32_32x32x16_bf16 v[48:63], v[74:77], v[124:127], v[48:63]
	ds_read_b64_tr_b16 v[124:125], v78 offset:0x2400
	ds_read_b64_tr_b16 v[126:127], v78 offset:0x2c00
	v_mfma_f32_32x32x16_bf16 v[48:63], v[112:115], v[128:131], v[48:63]
	ds_read_b64_tr_b16 v[128:129], v78 offset:0x3400
	ds_read_b64_tr_b16 v[130:131], v78 offset:0x3c00
	s_waitcnt lgkmcnt(0)
	v_mfma_f32_32x32x16_bf16 v[32:47], v[66:69], v[116:119], v[32:47]
	ds_read_b64_tr_b16 v[116:117], v78 offset:0x600
	ds_read_b64_tr_b16 v[118:119], v78 offset:0xe00
	v_mfma_f32_32x32x16_bf16 v[32:47], v[70:73], v[120:123], v[32:47]
	ds_read_b64_tr_b16 v[120:121], v78 offset:0x1600
	ds_read_b64_tr_b16 v[122:123], v78 offset:0x1e00
	v_mfma_f32_32x32x16_bf16 v[32:47], v[74:77], v[124:127], v[32:47]
	ds_read_b64_tr_b16 v[124:125], v78 offset:0x2600
	ds_read_b64_tr_b16 v[126:127], v78 offset:0x2e00
	v_mfma_f32_32x32x16_bf16 v[32:47], v[112:115], v[128:131], v[32:47]
	ds_read_b64_tr_b16 v[128:129], v78 offset:0x3600
	ds_read_b64_tr_b16 v[130:131], v78 offset:0x3e00
	s_waitcnt lgkmcnt(0)
	v_mfma_f32_32x32x16_bf16 v[16:31], v[66:69], v[116:119], v[16:31]
	v_max_f32_e32 v66, v97, v97
	v_max_f32_e32 v67, v96, v96
	v_max_f32_e32 v66, v67, v66
	v_max3_f32 v66, v66, v98, v99
	v_max3_f32 v66, v66, v100, v101
	v_max3_f32 v66, v66, v102, v103
	v_max3_f32 v66, v66, v104, v105
	v_mfma_f32_32x32x16_bf16 v[16:31], v[70:73], v[120:123], v[16:31]
	v_max3_f32 v66, v66, v106, v107
	v_max3_f32 v66, v66, v108, v109
	v_max3_f32 v66, v66, v110, v111
	v_max3_f32 v66, v66, v80, v81
	v_max3_f32 v66, v66, v82, v83
	v_max3_f32 v66, v66, v84, v85
	v_max3_f32 v66, v66, v86, v87
	v_mfma_f32_32x32x16_bf16 v[16:31], v[74:77], v[124:127], v[16:31]
	v_max3_f32 v66, v66, v88, v89
	v_max3_f32 v66, v66, v90, v91
	v_max3_f32 v66, v66, v92, v93
	v_max3_f32 v66, v66, v94, v95
	v_mov_b32_e32 v67, v66
	s_nop 1
	v_permlane32_swap_b32_e32 v66, v67
	v_mfma_f32_32x32x16_bf16 v[16:31], v[112:115], v[128:131], v[16:31]
	v_max_f32_e32 v67, v67, v67
	v_max_f32_e32 v66, v66, v66
	v_max_f32_e32 v67, v66, v67
	v_cmp_ge_f32_e32 vcc, s66, v67
	s_cmp_eq_u64 vcc, exec
	v_mov_b32_e32 v66, 1.0
	s_cbranch_scc0 .LBB0_1360
	v_cmp_gt_f32_e32 vcc, 1.0, v66
	s_cbranch_vccz .LBB0_1354

; #define SBAR() __builtin_amdgcn_sched_barrier(0)
; __device__ __forceinline__ void finishSM(f32x16& p0, f32x16& p1, float alpha, float& l_reg, bf16x8& pa0, bf16x8& pa1, bf16x8& pa2, bf16x8& pa3) {
; #pragma unroll
;   for (int r = 0; r < 16; ++r) p1[r] = __builtin_amdgcn_exp2f(p1[r]);
;   float ps = 0;
; #pragma unroll
;   for (int r = 0; r < 16; ++r) ps += p0[r];
; #pragma unroll
;   for (int r = 0; r < 16; ++r) ps += p1[r];
;   { auto rr = __builtin_amdgcn_permlane32_swap(__float_as_uint(ps), __float_as_uint(ps), false, false);
;     ps = __uint_as_float(rr[0]) + __uint_as_float(rr[1]); }
;   l_reg = l_reg * alpha + ps;
;     ...
;   PK4(p0, 0, pa0); PK4(p0, 8, pa1); PK4(p1, 0, pa2); PK4(p1, 8, pa3);
; __device__ __forceinline__ void attn_unit(const bf16_t* __restrict__ Qb, const bf16_t* __restrict__ Kh, const bf16_t* __restrict__ Vh, int seq, char* lds,
;                                           int mode, float* scratch, float lam, float gscale, const float* __restrict__ subg, bf16_t* outp) {
;     ...
;   finishSM(pB0, pB1, alB, l_reg, pa0, pa1, pa2, pa3); SBAR();
;   pv_d0(o, vb0 + bc * SHM_V, pa0, pa1, pa2, pa3);
;   __builtin_amdgcn_s_setprio(0);
;     ...
;   if (hi == 0) li_l[r32] = l_reg; asm volatile("s_waitcnt lgkmcnt(0)" ::: "memory");
;   float* sw = scratch + (long)(wid * QBLK) * 128;
;   if (mode == 0) {
.LBB0_1354:
	v_exp_f32_e32 v69, v96
	v_exp_f32_e32 v70, v97
	v_exp_f32_e32 v71, v98
	v_exp_f32_e32 v72, v99
	v_exp_f32_e32 v73, v100
	v_add_f32_e32 v67, 0, v69
	v_exp_f32_e32 v74, v101
	v_add_f32_e32 v67, v70, v67
	v_exp_f32_e32 v75, v102
	v_add_f32_e32 v67, v71, v67
	v_exp_f32_e32 v76, v103
	v_add_f32_e32 v67, v72, v67
	v_exp_f32_e32 v77, v104
	v_add_f32_e32 v67, v73, v67
	v_exp_f32_e32 v78, v105
	v_add_f32_e32 v67, v74, v67
	v_exp_f32_e32 v79, v106
	v_add_f32_e32 v67, v75, v67
	v_exp_f32_e32 v96, v107
	v_add_f32_e32 v67, v76, v67
	v_exp_f32_e32 v97, v108
	v_add_f32_e32 v67, v77, v67
	v_exp_f32_e32 v98, v109
	v_add_f32_e32 v67, v78, v67
	v_exp_f32_e32 v99, v110
	v_add_f32_e32 v67, v79, v67
	v_exp_f32_e32 v100, v111
	v_add_f32_e32 v67, v96, v67
	v_exp_f32_e32 v80, v80
	v_add_f32_e32 v67, v97, v67
	v_exp_f32_e32 v81, v81
	v_add_f32_e32 v67, v98, v67
	v_exp_f32_e32 v82, v82
	v_add_f32_e32 v67, v99, v67
	v_exp_f32_e32 v83, v83
	v_add_f32_e32 v67, v100, v67
	v_exp_f32_e32 v84, v84
	v_add_f32_e32 v67, v80, v67
	v_exp_f32_e32 v85, v85
	v_add_f32_e32 v67, v81, v67
	v_exp_f32_e32 v86, v86
	v_add_f32_e32 v67, v82, v67
	v_exp_f32_e32 v87, v87
	v_add_f32_e32 v67, v83, v67
	v_exp_f32_e32 v88, v88
	v_add_f32_e32 v67, v84, v67
	v_exp_f32_e32 v89, v89
	v_add_f32_e32 v67, v85, v67
	v_exp_f32_e32 v90, v90
	v_add_f32_e32 v67, v86, v67
	v_exp_f32_e32 v91, v91
	v_add_f32_e32 v67, v87, v67
	v_exp_f32_e32 v92, v92
	v_add_f32_e32 v67, v88, v67
	v_exp_f32_e32 v93, v93
	v_add_f32_e32 v67, v89, v67
	v_exp_f32_e32 v94, v94
	v_add_f32_e32 v67, v90, v67
	v_exp_f32_e32 v95, v95
	v_add_f32_e32 v67, v91, v67
	v_add_f32_e32 v67, v92, v67
	v_add_f32_e32 v67, v93, v67
	v_add_f32_e32 v67, v94, v67
	v_add_f32_e32 v67, v95, v67
	v_mov_b32_e32 v68, v67
	s_nop 1
	v_permlane32_swap_b32_e32 v67, v68
	v_cvt_pk_bf16_f32 v70, v69, v70
	v_cvt_pk_bf16_f32 v71, v71, v72
	v_cvt_pk_bf16_f32 v72, v73, v74
	v_cvt_pk_bf16_f32 v73, v75, v76
	v_cvt_pk_bf16_f32 v74, v77, v78
	v_cvt_pk_bf16_f32 v75, v79, v96
	v_cvt_pk_bf16_f32 v76, v97, v98
	v_cvt_pk_bf16_f32 v77, v99, v100
	v_cvt_pk_bf16_f32 v78, v80, v81
	v_cvt_pk_bf16_f32 v79, v82, v83
	v_cvt_pk_bf16_f32 v80, v84, v85
	v_cvt_pk_bf16_f32 v81, v86, v87
	v_cvt_pk_bf16_f32 v82, v88, v89
	v_cvt_pk_bf16_f32 v83, v90, v91
	v_cvt_pk_bf16_f32 v84, v92, v93
	v_cvt_pk_bf16_f32 v85, v94, v95
	s_nop 0
	s_nop 0
	s_nop 0
	s_nop 0
	s_nop 0
	s_nop 0
	s_nop 0
	s_nop 0
	s_nop 0
	ds_read_b64_tr_b16 v[86:87], v172 offset:0
	ds_read_b64_tr_b16 v[88:89], v172 offset:0x800
	ds_read_b64_tr_b16 v[90:91], v172 offset:0x1000
	ds_read_b64_tr_b16 v[92:93], v172 offset:0x1800
	ds_read_b64_tr_b16 v[94:95], v172 offset:0x2000
	ds_read_b64_tr_b16 v[96:97], v172 offset:0x2800
	ds_read_b64_tr_b16 v[98:99], v172 offset:0x3000
	ds_read_b64_tr_b16 v[100:101], v172 offset:0x3800
	s_waitcnt lgkmcnt(0)
	s_nop 0
	v_mfma_f32_32x32x16_bf16 v[0:15], v[70:73], v[86:89], v[0:15]
	ds_read_b64_tr_b16 v[86:87], v172 offset:0x200
	ds_read_b64_tr_b16 v[88:89], v172 offset:0xa00
	v_mfma_f32_32x32x16_bf16 v[0:15], v[74:77], v[90:93], v[0:15]
	ds_read_b64_tr_b16 v[90:91], v172 offset:0x1200
	ds_read_b64_tr_b16 v[92:93], v172 offset:0x1a00
	v_mfma_f32_32x32x16_bf16 v[0:15], v[78:81], v[94:97], v[0:15]
	ds_read_b64_tr_b16 v[94:95], v172 offset:0x2200
	ds_read_b64_tr_b16 v[96:97], v172 offset:0x2a00
	v_mfma_f32_32x32x16_bf16 v[0:15], v[82:85], v[98:101], v[0:15]
	ds_read_b64_tr_b16 v[98:99], v172 offset:0x3200
	ds_read_b64_tr_b16 v[100:101], v172 offset:0x3a00
	s_waitcnt lgkmcnt(0)
	v_mfma_f32_32x32x16_bf16 v[48:63], v[70:73], v[86:89], v[48:63]
	ds_read_b64_tr_b16 v[86:87], v172 offset:0x400
	ds_read_b64_tr_b16 v[88:89], v172 offset:0xc00
	v_mfma_f32_32x32x16_bf16 v[48:63], v[74:77], v[90:93], v[48:63]
	ds_read_b64_tr_b16 v[90:91], v172 offset:0x1400
	ds_read_b64_tr_b16 v[92:93], v172 offset:0x1c00
	v_mfma_f32_32x32x16_bf16 v[48:63], v[78:81], v[94:97], v[48:63]
	ds_read_b64_tr_b16 v[94:95], v172 offset:0x2400
	ds_read_b64_tr_b16 v[96:97], v172 offset:0x2c00
	v_mfma_f32_32x32x16_bf16 v[48:63], v[82:85], v[98:101], v[48:63]
	ds_read_b64_tr_b16 v[98:99], v172 offset:0x3400
	ds_read_b64_tr_b16 v[100:101], v172 offset:0x3c00
	s_waitcnt lgkmcnt(0)
	v_mfma_f32_32x32x16_bf16 v[32:47], v[70:73], v[86:89], v[32:47]
	ds_read_b64_tr_b16 v[86:87], v172 offset:0x600
	ds_read_b64_tr_b16 v[88:89], v172 offset:0xe00
	v_mfma_f32_32x32x16_bf16 v[32:47], v[74:77], v[90:93], v[32:47]
	ds_read_b64_tr_b16 v[90:91], v172 offset:0x1600
	ds_read_b64_tr_b16 v[92:93], v172 offset:0x1e00
	v_mfma_f32_32x32x16_bf16 v[32:47], v[78:81], v[94:97], v[32:47]
	ds_read_b64_tr_b16 v[94:95], v172 offset:0x2600
	ds_read_b64_tr_b16 v[96:97], v172 offset:0x2e00
	v_mfma_f32_32x32x16_bf16 v[32:47], v[82:85], v[98:101], v[32:47]
	ds_read_b64_tr_b16 v[98:99], v172 offset:0x3600
	ds_read_b64_tr_b16 v[100:101], v172 offset:0x3e00
	s_waitcnt lgkmcnt(0)
	v_mfma_f32_32x32x16_bf16 v[16:31], v[70:73], v[86:89], v[16:31]
	v_mfma_f32_32x32x16_bf16 v[16:31], v[74:77], v[90:93], v[16:31]
	v_mfma_f32_32x32x16_bf16 v[16:31], v[78:81], v[94:97], v[16:31]
	v_mfma_f32_32x32x16_bf16 v[16:31], v[82:85], v[98:101], v[16:31]
	s_setprio 0
	s_and_saveexec_b64 s[20:21], s[4:5]
	v_add_f32_e32 v64, v64, v65
	v_fmac_f32_e32 v64, v167, v158
	v_add_f32_e32 v65, v67, v68
	v_fmac_f32_e32 v65, v64, v66
	ds_write_b32 v153, v65
	s_or_b64 exec, exec, s[20:21]
	s_waitcnt lgkmcnt(0)
	v_ashrrev_i32_e32 v153, 31, v152
	v_lshlrev_b64 v[64:65], 9, v[152:153]
	v_lshlrev_b32_e32 v88, 2, v165
	v_lshl_add_u64 v[72:73], s[12:13], 0, v[64:65]
	s_mov_b64 s[4:5], -1
	s_and_b64 vcc, exec, s[72:73]
	v_lshl_add_u32 v86, v164, 4, v166
	v_lshl_or_b32 v178, v164, 11, v88
	s_cbranch_vccz .LBB0_1358
; __device__ __forceinline__ unsigned f2bf(float f) { return pk2(f, 0.f) & 0xffffu; }
; __device__ __forceinline__ float sum32(float v) { return swap16_sum(sum16(v)); }
; __device__ __forceinline__ int crow(int r, int hi) { return (r & 3) + 8 * (r >> 2) + 4 * hi; }
; __device__ __forceinline__ void attn_unit(const bf16_t* __restrict__ Qb, const bf16_t* __restrict__ Kh, const bf16_t* __restrict__ Vh, int seq, char* lds,
;                                           int mode, float* scratch, float lam, float gscale, const float* __restrict__ subg, bf16_t* outp) {
;     ...
;     bf16_t* ow = outp + (long)(wid * QBLK) * 1024;
;     float g4[4];
; #pragma unroll
;     for (int d0 = 0; d0 < 4; ++d0) g4[d0] = subg[d0 * 32 + r32] * gscale;
; #pragma unroll
;     for (int r = 0; r < 16; ++r) { const int orow = crow(r, hi); const float rl = __builtin_amdgcn_rcpf(li_l[orow]) * lam;
;       float x[4]; float ss = 0.f;
; #pragma unroll
;       for (int d0 = 0; d0 < 4; ++d0) { x[d0] = sw[orow * 128 + d0 * 32 + r32] - o[d0][r] * rl; ss += x[d0] * x[d0]; }
;       ss = sum32(ss);
;       const float rn = rsqrtf(ss * (1.f / 128.f) + 1e-6f);
; #pragma unroll
;       for (int d0 = 0; d0 < 4; ++d0) ow[orow * 1024 + d0 * 32 + r32] = (bf16_t)f2bf(x[d0] * rn * g4[d0]); }
	v_lshl_add_u64 v[64:65], v[72:73], 0, v[178:179]
	global_load_dword v111, v88, s[14:15]
	global_load_dword v112, v88, s[14:15] offset:128
	global_load_dword v68, v[64:65], off
	global_load_dword v69, v[64:65], off offset:128
	global_load_dword v71, v[64:65], off offset:256
	global_load_dword v70, v[64:65], off offset:384
	v_lshlrev_b32_e32 v89, 2, v164
	v_or_b32_e32 v113, 1, v89
	v_lshl_or_b32 v64, v113, 9, v88
	v_mov_b32_e32 v65, v179
	v_lshl_add_u64 v[64:65], v[72:73], 0, v[64:65]
	global_load_dword v78, v[64:65], off
	global_load_dword v79, v[64:65], off offset:128
	global_load_dword v81, v[64:65], off offset:256
	global_load_dword v80, v[64:65], off offset:384
	global_load_dword v114, v88, s[14:15] offset:256
	global_load_dword v115, v88, s[14:15] offset:384
	ds_read_b128 v[82:85], v86
	ds_read_b128 v[64:67], v86 offset:32
	v_lshlrev_b64 v[76:77], 11, v[152:153]
	v_lshlrev_b32_e32 v87, 1, v165
	v_or_b32_e32 v116, 2, v89
	v_mov_b32_e32 v91, v179
	v_mov_b32_e32 v101, v179
	v_lshl_add_u64 v[76:77], s[22:23], 0, v[76:77]
	v_lshl_or_b32 v90, v164, 13, v87
	v_or_b32_e32 v117, 3, v89
	v_lshl_or_b32 v100, v116, 9, v88
	v_mov_b32_e32 v103, v179
	v_lshl_add_u64 v[104:105], v[76:77], 0, v[90:91]
	v_lshl_or_b32 v102, v117, 9, v88
	v_lshl_add_u64 v[90:91], v[72:73], 0, v[100:101]
	v_lshl_add_u64 v[100:101], v[72:73], 0, v[102:103]
	s_waitcnt lgkmcnt(1)
	v_rcp_f32_e32 v110, v82
	v_rcp_f32_e32 v118, v83
	global_load_dword v82, v[90:91], off
	global_load_dword v83, v[90:91], off offset:128
	global_load_dword v103, v[90:91], off offset:256
	global_load_dword v102, v[90:91], off offset:384
	global_load_dword v106, v[100:101], off
	global_load_dword v107, v[100:101], off offset:128
	global_load_dword v109, v[100:101], off offset:256
	global_load_dword v108, v[100:101], off offset:384
	v_mov_b32_e32 v92, v0
	v_mov_b32_e32 v93, v48
	v_mul_f32_e32 v100, v163, v110
	v_mov_b32_e32 v94, v16
	v_mov_b32_e32 v95, v32
	v_mov_b32_e32 v96, v1
	v_mov_b32_e32 v97, v49
	v_mul_f32_e32 v110, v163, v118
	v_mov_b32_e32 v98, v17
	v_mov_b32_e32 v99, v33
	s_mov_b32 s0, 0x358637bd
	v_mov_b64_e32 v[74:75], s[0:1]
	s_waitcnt lgkmcnt(0)
	v_rcp_f32_e32 v64, v64
	v_rcp_f32_e32 v66, v66
	s_mov_b64 s[4:5], 0
	v_mul_f32_e32 v64, v163, v64
	s_waitcnt vmcnt(16)
	v_pk_fma_f32 v[68:69], v[92:93], v[100:101], v[68:69] op_sel_hi:[1,0,1] neg_lo:[1,0,0] neg_hi:[1,0,0]
	s_nop 0
	v_pk_mul_f32 v[92:93], v[68:69], v[68:69]
	s_waitcnt vmcnt(14)
	v_pk_fma_f32 v[70:71], v[94:95], v[100:101], v[70:71] op_sel_hi:[1,0,1] neg_lo:[1,0,0] neg_hi:[1,0,0]
	v_add_f32_e32 v92, v92, v93
	v_pk_mul_f32 v[94:95], v[70:71], v[70:71]
	s_waitcnt vmcnt(12)
	v_pk_fma_f32 v[78:79], v[96:97], v[110:111], v[78:79] op_sel_hi:[1,0,1] neg_lo:[1,0,0] neg_hi:[1,0,0]
	v_add_f32_e32 v92, v95, v92
	s_waitcnt vmcnt(10)
	v_pk_fma_f32 v[80:81], v[98:99], v[110:111], v[80:81] op_sel_hi:[1,0,1] neg_lo:[1,0,0] neg_hi:[1,0,0]
	v_add_f32_e32 v96, v94, v92
	v_pk_mul_f32 v[92:93], v[78:79], v[78:79]
	v_pk_mul_f32 v[94:95], v[80:81], v[80:81]
	v_add_f32_e32 v92, v92, v93
	v_add_f32_e32 v92, v95, v92
	v_add_f32_e32 v92, v94, v92
	v_add_f32_dpp v96, v96, v96 quad_perm:[1,0,3,2] row_mask:0xf bank_mask:0xf bound_ctrl:1
	v_mul_f32_e32 v91, v162, v111
	v_add_f32_dpp v92, v92, v92 quad_perm:[1,0,3,2] row_mask:0xf bank_mask:0xf bound_ctrl:1
	v_add_f32_dpp v93, v96, v96 quad_perm:[2,3,0,1] row_mask:0xf bank_mask:0xf bound_ctrl:1
	v_mul_f32_e32 v90, v162, v112
	v_add_f32_dpp v92, v92, v92 quad_perm:[2,3,0,1] row_mask:0xf bank_mask:0xf bound_ctrl:1
	v_add_f32_dpp v93, v93, v93 row_half_mirror row_mask:0xf bank_mask:0xf bound_ctrl:1
	s_nop 0
	v_add_f32_dpp v92, v92, v92 row_half_mirror row_mask:0xf bank_mask:0xf bound_ctrl:1
	v_add_f32_dpp v93, v93, v93 row_mirror row_mask:0xf bank_mask:0xf bound_ctrl:1
	v_mov_b32_e32 v95, v93
	v_add_f32_dpp v92, v92, v92 row_mirror row_mask:0xf bank_mask:0xf bound_ctrl:1
	v_mov_b32_e32 v94, v92
	v_permlane16_swap_b32_e32 v93, v95
	s_nop 0
	v_permlane16_swap_b32_e32 v92, v94
	v_pk_add_f32 v[92:93], v[92:93], v[94:95]
	s_nop 0
	v_pk_fma_f32 v[94:95], v[92:93], s[62:63], v[74:75] op_sel_hi:[1,0,0]
	s_waitcnt vmcnt(9)
	v_mul_f32_e32 v93, v162, v114
	v_mul_f32_e32 v92, 0x4b800000, v95
	v_cmp_gt_f32_e32 vcc, s33, v95
	v_mul_f32_e32 v96, 0x4b800000, v94
	s_nop 0
	v_cndmask_b32_e32 v92, v95, v92, vcc
	v_rsq_f32_e32 v95, v92
	s_waitcnt vmcnt(8)
	v_mul_f32_e32 v92, v162, v115
	v_mul_f32_e32 v97, 0x45800000, v95
	v_cndmask_b32_e32 v95, v95, v97, vcc
	v_mul_f32_e32 v68, v68, v95
	v_mul_f32_e32 v69, v69, v95
	v_mul_f32_e32 v71, v71, v95
	v_mul_f32_e32 v68, v91, v68
	v_mul_f32_e32 v69, v90, v69
	v_mul_f32_e32 v71, v93, v71
	v_cvt_pk_bf16_f32 v68, v68, s0
	v_cmp_gt_f32_e32 vcc, s33, v94
	v_cvt_pk_bf16_f32 v69, v69, s0
	v_cvt_pk_bf16_f32 v71, v71, s0
	global_store_short v[104:105], v68, off
	global_store_short v[104:105], v69, off offset:64
	global_store_short v[104:105], v71, off offset:128
	v_cndmask_b32_e32 v68, v94, v96, vcc
	v_rsq_f32_e32 v68, v68
	v_mul_f32_e32 v70, v70, v95
	v_mul_f32_e32 v69, v92, v70
	v_cvt_pk_bf16_f32 v69, v69, s0
	global_store_short v[104:105], v69, off offset:192
	v_mul_f32_e32 v69, 0x45800000, v68
	v_cndmask_b32_e32 v70, v68, v69, vcc
	v_mul_f32_e32 v68, v78, v70
	v_mul_f32_e32 v68, v91, v68
	v_cvt_pk_bf16_f32 v71, v68, s0
	v_lshl_or_b32 v68, v113, 11, v87
	v_mov_b32_e32 v69, v179
	v_lshl_add_u64 v[68:69], v[76:77], 0, v[68:69]
	global_store_short v[68:69], v71, off
	v_mul_f32_e32 v71, v79, v70
	v_mul_f32_e32 v71, v90, v71
	v_cvt_pk_bf16_f32 v71, v71, s0
	global_store_short v[68:69], v71, off offset:64
	v_mul_f32_e32 v71, v81, v70
	v_mul_f32_e32 v71, v93, v71
	v_cvt_pk_bf16_f32 v71, v71, s0
	global_store_short v[68:69], v71, off offset:128
	v_rcp_f32_e32 v71, v84
	v_mul_f32_e32 v70, v80, v70
	v_mul_f32_e32 v70, v92, v70
	v_cvt_pk_bf16_f32 v70, v70, s0
	global_store_short v[68:69], v70, off offset:192
	v_mul_f32_e32 v68, v163, v71
	v_mov_b32_e32 v70, v2
	v_mov_b32_e32 v71, v50
	s_waitcnt vmcnt(14)
; __device__ __forceinline__ unsigned f2bf(float f) { return pk2(f, 0.f) & 0xffffu; }
; __device__ __forceinline__ float sum32(float v) { return swap16_sum(sum16(v)); }
; __device__ __forceinline__ int crow(int r, int hi) { return (r & 3) + 8 * (r >> 2) + 4 * hi; }
; __device__ __forceinline__ void attn_unit(const bf16_t* __restrict__ Qb, const bf16_t* __restrict__ Kh, const bf16_t* __restrict__ Vh, int seq, char* lds,
;                                           int mode, float* scratch, float lam, float gscale, const float* __restrict__ subg, bf16_t* outp) {
;     ...
;     bf16_t* ow = outp + (long)(wid * QBLK) * 1024;
;     float g4[4];
; #pragma unroll
;     for (int d0 = 0; d0 < 4; ++d0) g4[d0] = subg[d0 * 32 + r32] * gscale;
; #pragma unroll
;     for (int r = 0; r < 16; ++r) { const int orow = crow(r, hi); const float rl = __builtin_amdgcn_rcpf(li_l[orow]) * lam;
;       float x[4]; float ss = 0.f;
; #pragma unroll
;       for (int d0 = 0; d0 < 4; ++d0) { x[d0] = sw[orow * 128 + d0 * 32 + r32] - o[d0][r] * rl; ss += x[d0] * x[d0]; }
;       ss = sum32(ss);
;       const float rn = rsqrtf(ss * (1.f / 128.f) + 1e-6f);
; #pragma unroll
;       for (int d0 = 0; d0 < 4; ++d0) ow[orow * 1024 + d0 * 32 + r32] = (bf16_t)f2bf(x[d0] * rn * g4[d0]); }
	v_pk_fma_f32 v[70:71], v[70:71], v[68:69], v[82:83] op_sel_hi:[1,0,1] neg_lo:[1,0,0] neg_hi:[1,0,0]
	v_mov_b32_e32 v80, v18
	v_mov_b32_e32 v81, v34
	v_pk_mul_f32 v[78:79], v[70:71], v[70:71]
	s_waitcnt vmcnt(12)
	v_pk_fma_f32 v[68:69], v[80:81], v[68:69], v[102:103] op_sel_hi:[1,0,1] neg_lo:[1,0,0] neg_hi:[1,0,0]
	v_add_f32_e32 v78, v78, v79
	v_pk_mul_f32 v[80:81], v[68:69], v[68:69]
	v_mov_b32_e32 v82, v3
	v_add_f32_e32 v78, v81, v78
	v_add_f32_e32 v78, v80, v78
	v_mov_b32_e32 v83, v51
	v_or_b32_e32 v104, 8, v89
	v_add_f32_dpp v78, v78, v78 quad_perm:[1,0,3,2] row_mask:0xf bank_mask:0xf bound_ctrl:1
	v_mov_b32_e32 v94, v19
	v_lshl_or_b32 v96, v104, 9, v88
	v_add_f32_dpp v78, v78, v78 quad_perm:[2,3,0,1] row_mask:0xf bank_mask:0xf bound_ctrl:1
	v_mov_b32_e32 v97, v179
	v_mov_b32_e32 v95, v35
	v_add_f32_dpp v78, v78, v78 row_half_mirror row_mask:0xf bank_mask:0xf bound_ctrl:1
	v_lshl_add_u64 v[96:97], v[72:73], 0, v[96:97]
	global_load_dword v98, v[96:97], off
	global_load_dword v99, v[96:97], off offset:128
	v_add_f32_dpp v79, v78, v78 row_mirror row_mask:0xf bank_mask:0xf bound_ctrl:1
	v_rcp_f32_e32 v78, v85
	v_mov_b32_e32 v81, v79
	s_nop 1
	v_permlane16_swap_b32_e32 v79, v81
	v_mul_f32_e32 v78, v163, v78
	s_waitcnt vmcnt(12)
	v_pk_fma_f32 v[82:83], v[82:83], v[78:79], v[106:107] op_sel_hi:[1,0,1] neg_lo:[1,0,0] neg_hi:[1,0,0]
	s_waitcnt vmcnt(10)
	v_pk_fma_f32 v[94:95], v[94:95], v[78:79], v[108:109] op_sel_hi:[1,0,1] neg_lo:[1,0,0] neg_hi:[1,0,0]
	v_pk_mul_f32 v[84:85], v[82:83], v[82:83]
	global_load_dword v101, v[96:97], off offset:256
	global_load_dword v100, v[96:97], off offset:384
	v_pk_mul_f32 v[96:97], v[94:95], v[94:95]
	v_add_f32_e32 v78, v84, v85
	v_add_f32_e32 v78, v97, v78
	v_add_f32_e32 v78, v96, v78
	v_or_b32_e32 v105, 9, v89
	v_mov_b32_e32 v97, v179
	v_add_f32_dpp v78, v78, v78 quad_perm:[1,0,3,2] row_mask:0xf bank_mask:0xf bound_ctrl:1
	v_or_b32_e32 v106, 17, v89
	v_or_b32_e32 v107, 18, v89
	v_add_f32_dpp v78, v78, v78 quad_perm:[2,3,0,1] row_mask:0xf bank_mask:0xf bound_ctrl:1
	v_or_b32_e32 v108, 19, v89
	s_nop 0
	v_add_f32_dpp v78, v78, v78 row_half_mirror row_mask:0xf bank_mask:0xf bound_ctrl:1
	s_nop 1
	v_add_f32_dpp v78, v78, v78 row_mirror row_mask:0xf bank_mask:0xf bound_ctrl:1
	v_mov_b32_e32 v80, v78
	s_nop 1
	v_permlane16_swap_b32_e32 v78, v80
	v_pk_add_f32 v[78:79], v[78:79], v[80:81]
	v_lshl_or_b32 v80, v105, 9, v88
	v_pk_fma_f32 v[78:79], v[78:79], s[62:63], v[74:75] op_sel_hi:[1,0,0]
	v_mov_b32_e32 v81, v179
	v_mul_f32_e32 v96, 0x4b800000, v79
	v_cmp_gt_f32_e32 vcc, s33, v79
	v_lshl_add_u64 v[80:81], v[72:73], 0, v[80:81]
	global_load_dword v84, v[80:81], off
	global_load_dword v85, v[80:81], off offset:128
	v_cndmask_b32_e32 v79, v79, v96, vcc
	v_rsq_f32_e32 v79, v79
	v_lshl_or_b32 v96, v116, 11, v87
	v_lshl_add_u64 v[96:97], v[76:77], 0, v[96:97]
	v_mul_f32_e32 v102, 0x45800000, v79
	v_cndmask_b32_e32 v79, v79, v102, vcc
	global_load_dword v103, v[80:81], off offset:256
	global_load_dword v102, v[80:81], off offset:384
	v_mul_f32_e32 v69, v69, v79
	v_mul_f32_e32 v69, v93, v69
	v_cvt_pk_bf16_f32 v69, v69, s0
	global_store_short v[96:97], v69, off offset:128
	v_mul_f32_e32 v69, 0x4b800000, v78
	v_cmp_gt_f32_e32 vcc, s33, v78
	v_mul_f32_e32 v70, v70, v79
	v_mul_f32_e32 v70, v91, v70
	v_cndmask_b32_e32 v69, v78, v69, vcc
	v_rsq_f32_e32 v69, v69
	v_cvt_pk_bf16_f32 v70, v70, s0
	v_mul_f32_e32 v68, v68, v79
	global_store_short v[96:97], v70, off
	v_mul_f32_e32 v70, v71, v79
	v_mul_f32_e32 v68, v92, v68
	v_mul_f32_e32 v70, v90, v70
	v_cvt_pk_bf16_f32 v68, v68, s0
	v_cvt_pk_bf16_f32 v70, v70, s0
	global_store_short v[96:97], v68, off offset:192
	v_mul_f32_e32 v68, 0x45800000, v69
	global_store_short v[96:97], v70, off offset:64
	v_cndmask_b32_e32 v70, v69, v68, vcc
	v_mul_f32_e32 v68, v82, v70
	v_mul_f32_e32 v68, v91, v68
	v_cvt_pk_bf16_f32 v71, v68, s0
	v_lshl_or_b32 v68, v117, 11, v87
	v_mov_b32_e32 v69, v179
	v_lshl_add_u64 v[68:69], v[76:77], 0, v[68:69]
	global_store_short v[68:69], v71, off
	v_mul_f32_e32 v71, v83, v70
	v_mul_f32_e32 v71, v90, v71
	v_cvt_pk_bf16_f32 v71, v71, s0
	global_store_short v[68:69], v71, off offset:64
	v_mul_f32_e32 v71, v95, v70
	v_mul_f32_e32 v70, v94, v70
	v_mul_f32_e32 v71, v93, v71
	v_mul_f32_e32 v70, v92, v70
	v_cvt_pk_bf16_f32 v71, v71, s0
	v_cvt_pk_bf16_f32 v70, v70, s0
	global_store_short v[68:69], v71, off offset:128
	global_store_short v[68:69], v70, off offset:192
	v_mov_b32_e32 v68, v4
	v_mov_b32_e32 v69, v52
	s_waitcnt vmcnt(14)
	v_pk_fma_f32 v[68:69], v[68:69], v[64:65], v[98:99] op_sel_hi:[1,0,1] neg_lo:[1,0,0] neg_hi:[1,0,0]
	v_mov_b32_e32 v78, v20
	v_mov_b32_e32 v79, v36
	v_pk_mul_f32 v[70:71], v[68:69], v[68:69]
	s_waitcnt vmcnt(12)
	v_pk_fma_f32 v[78:79], v[78:79], v[64:65], v[100:101] op_sel_hi:[1,0,1] neg_lo:[1,0,0] neg_hi:[1,0,0]
	v_add_f32_e32 v64, v70, v71
	v_pk_mul_f32 v[80:81], v[78:79], v[78:79]
	v_rcp_f32_e32 v70, v65
	v_add_f32_e32 v64, v81, v64
	v_add_f32_e32 v64, v80, v64
	v_mov_b32_e32 v82, v5
	v_mul_f32_e32 v70, v163, v70
	v_add_f32_dpp v64, v64, v64 quad_perm:[1,0,3,2] row_mask:0xf bank_mask:0xf bound_ctrl:1
	v_mov_b32_e32 v83, v53
	v_mov_b32_e32 v98, v21
	v_add_f32_dpp v64, v64, v64 quad_perm:[2,3,0,1] row_mask:0xf bank_mask:0xf bound_ctrl:1
	v_mov_b32_e32 v99, v37
	v_mov_b32_e32 v65, v179
	v_add_f32_dpp v64, v64, v64 row_half_mirror row_mask:0xf bank_mask:0xf bound_ctrl:1
	s_nop 1
	v_add_f32_dpp v71, v64, v64 row_mirror row_mask:0xf bank_mask:0xf bound_ctrl:1
	v_mov_b32_e32 v81, v71
	s_nop 1
	v_permlane16_swap_b32_e32 v71, v81
	v_lshl_or_b32 v64, v104, 11, v87
	v_or_b32_e32 v104, 10, v89
	v_lshl_add_u64 v[64:65], v[76:77], 0, v[64:65]
	s_waitcnt vmcnt(10)
; __device__ __forceinline__ unsigned f2bf(float f) { return pk2(f, 0.f) & 0xffffu; }
; __device__ __forceinline__ float sum32(float v) { return swap16_sum(sum16(v)); }
; __device__ __forceinline__ int crow(int r, int hi) { return (r & 3) + 8 * (r >> 2) + 4 * hi; }
; __device__ __forceinline__ void attn_unit(const bf16_t* __restrict__ Qb, const bf16_t* __restrict__ Kh, const bf16_t* __restrict__ Vh, int seq, char* lds,
;                                           int mode, float* scratch, float lam, float gscale, const float* __restrict__ subg, bf16_t* outp) {
;     ...
;     bf16_t* ow = outp + (long)(wid * QBLK) * 1024;
;     float g4[4];
; #pragma unroll
;     for (int d0 = 0; d0 < 4; ++d0) g4[d0] = subg[d0 * 32 + r32] * gscale;
; #pragma unroll
;     for (int r = 0; r < 16; ++r) { const int orow = crow(r, hi); const float rl = __builtin_amdgcn_rcpf(li_l[orow]) * lam;
;       float x[4]; float ss = 0.f;
; #pragma unroll
;       for (int d0 = 0; d0 < 4; ++d0) { x[d0] = sw[orow * 128 + d0 * 32 + r32] - o[d0][r] * rl; ss += x[d0] * x[d0]; }
;       ss = sum32(ss);
;       const float rn = rsqrtf(ss * (1.f / 128.f) + 1e-6f);
; #pragma unroll
;       for (int d0 = 0; d0 < 4; ++d0) ow[orow * 1024 + d0 * 32 + r32] = (bf16_t)f2bf(x[d0] * rn * g4[d0]); }
	v_pk_fma_f32 v[82:83], v[82:83], v[70:71], v[84:85] op_sel_hi:[1,0,1] neg_lo:[1,0,0] neg_hi:[1,0,0]
	v_lshl_or_b32 v84, v104, 9, v88
	v_mov_b32_e32 v85, v179
	v_lshl_add_u64 v[84:85], v[72:73], 0, v[84:85]
	global_load_dword v94, v[84:85], off
	global_load_dword v95, v[84:85], off offset:128
	v_pk_mul_f32 v[96:97], v[82:83], v[82:83]
	global_load_dword v101, v[84:85], off offset:256
	global_load_dword v100, v[84:85], off offset:384
	s_waitcnt vmcnt(12)
	v_pk_fma_f32 v[84:85], v[98:99], v[70:71], v[102:103] op_sel_hi:[1,0,1] neg_lo:[1,0,0] neg_hi:[1,0,0]
	s_nop 0
	v_pk_mul_f32 v[98:99], v[84:85], v[84:85]
	v_add_f32_e32 v70, v96, v97
	v_add_f32_e32 v70, v99, v70
	v_add_f32_e32 v70, v98, v70
	v_or_b32_e32 v102, 11, v89
	v_lshl_or_b32 v96, v102, 9, v88
	v_add_f32_dpp v70, v70, v70 quad_perm:[1,0,3,2] row_mask:0xf bank_mask:0xf bound_ctrl:1
	v_mov_b32_e32 v97, v179
	v_lshl_add_u64 v[96:97], v[72:73], 0, v[96:97]
	v_add_f32_dpp v70, v70, v70 quad_perm:[2,3,0,1] row_mask:0xf bank_mask:0xf bound_ctrl:1
	global_load_dword v98, v[96:97], off
	global_load_dword v99, v[96:97], off offset:128
	v_add_f32_dpp v70, v70, v70 row_half_mirror row_mask:0xf bank_mask:0xf bound_ctrl:1
	s_nop 1
	v_add_f32_dpp v70, v70, v70 row_mirror row_mask:0xf bank_mask:0xf bound_ctrl:1
	v_mov_b32_e32 v80, v70
	s_nop 1
	v_permlane16_swap_b32_e32 v70, v80
	v_pk_add_f32 v[70:71], v[70:71], v[80:81]
	s_nop 0
	v_pk_fma_f32 v[70:71], v[70:71], s[62:63], v[74:75] op_sel_hi:[1,0,0]
	s_nop 0
	v_mul_f32_e32 v80, 0x4b800000, v71
	v_cmp_gt_f32_e32 vcc, s33, v71
	s_nop 1
	v_cndmask_b32_e32 v71, v71, v80, vcc
	global_load_dword v81, v[96:97], off offset:256
	global_load_dword v80, v[96:97], off offset:384
	v_rsq_f32_e32 v71, v71
	v_mov_b32_e32 v97, v39
	v_mul_f32_e32 v96, 0x45800000, v71
	v_cndmask_b32_e32 v71, v71, v96, vcc
	v_mul_f32_e32 v68, v68, v71
	v_mul_f32_e32 v68, v91, v68
	v_cvt_pk_bf16_f32 v68, v68, s0
	global_store_short v[64:65], v68, off
	v_mul_f32_e32 v68, v69, v71
	v_mul_f32_e32 v68, v90, v68
	v_cvt_pk_bf16_f32 v68, v68, s0
	global_store_short v[64:65], v68, off offset:64
	v_mul_f32_e32 v68, v79, v71
	v_mul_f32_e32 v69, 0x4b800000, v70
	v_cmp_gt_f32_e32 vcc, s33, v70
	v_mul_f32_e32 v68, v93, v68
	v_cvt_pk_bf16_f32 v68, v68, s0
	v_cndmask_b32_e32 v69, v70, v69, vcc
	v_rsq_f32_e32 v69, v69
	global_store_short v[64:65], v68, off offset:128
	v_mul_f32_e32 v68, v78, v71
	v_mul_f32_e32 v68, v92, v68
	v_cvt_pk_bf16_f32 v68, v68, s0
	global_store_short v[64:65], v68, off offset:192
	v_mul_f32_e32 v64, 0x45800000, v69
	v_cndmask_b32_e32 v68, v69, v64, vcc
	v_mul_f32_e32 v64, v82, v68
	v_mul_f32_e32 v64, v91, v64
	v_cvt_pk_bf16_f32 v69, v64, s0
	v_lshl_or_b32 v64, v105, 11, v87
	v_mov_b32_e32 v65, v179
	v_lshl_add_u64 v[64:65], v[76:77], 0, v[64:65]
	global_store_short v[64:65], v69, off
	v_mul_f32_e32 v69, v83, v68
	v_mul_f32_e32 v69, v90, v69
	v_cvt_pk_bf16_f32 v69, v69, s0
	global_store_short v[64:65], v69, off offset:64
	v_mul_f32_e32 v69, v85, v68
	v_mul_f32_e32 v68, v84, v68
	v_mul_f32_e32 v69, v93, v69
	v_mul_f32_e32 v68, v92, v68
	v_cvt_pk_bf16_f32 v69, v69, s0
	v_cvt_pk_bf16_f32 v68, v68, s0
	global_store_short v[64:65], v69, off offset:128
	global_store_short v[64:65], v68, off offset:192
	v_mul_f32_e32 v64, v163, v66
	v_mov_b32_e32 v68, v6
	v_mov_b32_e32 v69, v54
	s_waitcnt vmcnt(14)
	v_pk_fma_f32 v[68:69], v[68:69], v[64:65], v[94:95] op_sel_hi:[1,0,1] neg_lo:[1,0,0] neg_hi:[1,0,0]
	v_mov_b32_e32 v78, v22
	v_mov_b32_e32 v79, v38
	v_pk_mul_f32 v[70:71], v[68:69], v[68:69]
	s_waitcnt vmcnt(12)
	v_pk_fma_f32 v[64:65], v[78:79], v[64:65], v[100:101] op_sel_hi:[1,0,1] neg_lo:[1,0,0] neg_hi:[1,0,0]
	v_add_f32_e32 v66, v70, v71
	v_pk_mul_f32 v[78:79], v[64:65], v[64:65]
	v_rcp_f32_e32 v70, v67
	v_add_f32_e32 v66, v79, v66
	v_add_f32_e32 v66, v78, v66
	v_mov_b32_e32 v78, v7
	v_mul_f32_e32 v70, v163, v70
	v_add_f32_dpp v66, v66, v66 quad_perm:[1,0,3,2] row_mask:0xf bank_mask:0xf bound_ctrl:1
	v_mov_b32_e32 v79, v55
	v_mov_b32_e32 v96, v23
	v_add_f32_dpp v66, v66, v66 quad_perm:[2,3,0,1] row_mask:0xf bank_mask:0xf bound_ctrl:1
	v_mov_b32_e32 v67, v179
	v_lshl_or_b32 v100, v107, 9, v88
	v_add_f32_dpp v66, v66, v66 row_half_mirror row_mask:0xf bank_mask:0xf bound_ctrl:1
	v_mov_b32_e32 v101, v179
	v_lshl_add_u64 v[100:101], v[72:73], 0, v[100:101]
	v_add_f32_dpp v71, v66, v66 row_mirror row_mask:0xf bank_mask:0xf bound_ctrl:1
	v_mov_b32_e32 v85, v71
	s_nop 1
	v_permlane16_swap_b32_e32 v71, v85
	v_lshl_or_b32 v66, v104, 11, v87
	v_or_b32_e32 v104, 16, v89
	s_waitcnt vmcnt(10)
	v_pk_fma_f32 v[94:95], v[78:79], v[70:71], v[98:99] op_sel_hi:[1,0,1] neg_lo:[1,0,0] neg_hi:[1,0,0]
	v_lshl_or_b32 v78, v104, 9, v88
	v_mov_b32_e32 v79, v179
	v_lshl_add_u64 v[98:99], v[72:73], 0, v[78:79]
	global_load_dword v78, v[98:99], off
	global_load_dword v79, v[98:99], off offset:128
	v_pk_mul_f32 v[82:83], v[94:95], v[94:95]
	s_waitcnt vmcnt(10)
; __device__ __forceinline__ unsigned f2bf(float f) { return pk2(f, 0.f) & 0xffffu; }
; __device__ __forceinline__ float sum32(float v) { return swap16_sum(sum16(v)); }
; __device__ __forceinline__ int crow(int r, int hi) { return (r & 3) + 8 * (r >> 2) + 4 * hi; }
; __device__ __forceinline__ void attn_unit(const bf16_t* __restrict__ Qb, const bf16_t* __restrict__ Kh, const bf16_t* __restrict__ Vh, int seq, char* lds,
;                                           int mode, float* scratch, float lam, float gscale, const float* __restrict__ subg, bf16_t* outp) {
;     ...
;     bf16_t* ow = outp + (long)(wid * QBLK) * 1024;
;     float g4[4];
; #pragma unroll
;     for (int d0 = 0; d0 < 4; ++d0) g4[d0] = subg[d0 * 32 + r32] * gscale;
; #pragma unroll
;     for (int r = 0; r < 16; ++r) { const int orow = crow(r, hi); const float rl = __builtin_amdgcn_rcpf(li_l[orow]) * lam;
;       float x[4]; float ss = 0.f;
; #pragma unroll
;       for (int d0 = 0; d0 < 4; ++d0) { x[d0] = sw[orow * 128 + d0 * 32 + r32] - o[d0][r] * rl; ss += x[d0] * x[d0]; }
;       ss = sum32(ss);
;       const float rn = rsqrtf(ss * (1.f / 128.f) + 1e-6f);
; #pragma unroll
;       for (int d0 = 0; d0 < 4; ++d0) ow[orow * 1024 + d0 * 32 + r32] = (bf16_t)f2bf(x[d0] * rn * g4[d0]); }
	v_pk_fma_f32 v[96:97], v[96:97], v[70:71], v[80:81] op_sel_hi:[1,0,1] neg_lo:[1,0,0] neg_hi:[1,0,0]
	global_load_dword v81, v[98:99], off offset:256
	global_load_dword v80, v[98:99], off offset:384
	v_pk_mul_f32 v[98:99], v[96:97], v[96:97]
	v_add_f32_e32 v70, v82, v83
	v_add_f32_e32 v70, v99, v70
	v_add_f32_e32 v70, v98, v70
	v_lshl_or_b32 v82, v106, 9, v88
	v_mov_b32_e32 v83, v179
	v_add_f32_dpp v70, v70, v70 quad_perm:[1,0,3,2] row_mask:0xf bank_mask:0xf bound_ctrl:1
	v_lshl_add_u64 v[98:99], v[72:73], 0, v[82:83]
	global_load_dword v82, v[98:99], off
	global_load_dword v83, v[98:99], off offset:128
	v_add_f32_dpp v70, v70, v70 quad_perm:[2,3,0,1] row_mask:0xf bank_mask:0xf bound_ctrl:1
	v_lshl_add_u64 v[66:67], v[76:77], 0, v[66:67]
	s_nop 0
	v_add_f32_dpp v70, v70, v70 row_half_mirror row_mask:0xf bank_mask:0xf bound_ctrl:1
	s_nop 1
	v_add_f32_dpp v70, v70, v70 row_mirror row_mask:0xf bank_mask:0xf bound_ctrl:1
	v_mov_b32_e32 v84, v70
	s_nop 1
	v_permlane16_swap_b32_e32 v70, v84
	v_pk_add_f32 v[70:71], v[70:71], v[84:85]
	s_nop 0
	v_pk_fma_f32 v[70:71], v[70:71], s[62:63], v[74:75] op_sel_hi:[1,0,0]
	s_nop 0
	v_mul_f32_e32 v84, 0x4b800000, v71
	v_cmp_gt_f32_e32 vcc, s33, v71
	s_nop 1
	v_cndmask_b32_e32 v71, v71, v84, vcc
	global_load_dword v85, v[98:99], off offset:256
	global_load_dword v84, v[98:99], off offset:384
	v_rsq_f32_e32 v71, v71
	s_nop 0
	v_mul_f32_e32 v98, 0x45800000, v71
	v_cndmask_b32_e32 v71, v71, v98, vcc
	v_mul_f32_e32 v65, v65, v71
	v_mul_f32_e32 v65, v93, v65
	v_cvt_pk_bf16_f32 v65, v65, s0
	global_store_short v[66:67], v65, off offset:128
	v_mul_f32_e32 v65, 0x4b800000, v70
	v_cmp_gt_f32_e32 vcc, s33, v70
	v_mul_f32_e32 v68, v68, v71
	v_mul_f32_e32 v68, v91, v68
	v_cndmask_b32_e32 v65, v70, v65, vcc
	v_rsq_f32_e32 v65, v65
	v_cvt_pk_bf16_f32 v68, v68, s0
	v_mul_f32_e32 v64, v64, v71
	global_store_short v[66:67], v68, off
	v_mul_f32_e32 v68, v69, v71
	v_mul_f32_e32 v64, v92, v64
	v_mul_f32_e32 v68, v90, v68
	v_cvt_pk_bf16_f32 v64, v64, s0
	v_cvt_pk_bf16_f32 v68, v68, s0
	global_store_short v[66:67], v64, off offset:192
	v_mul_f32_e32 v64, 0x45800000, v65
	global_store_short v[66:67], v68, off offset:64
	v_cndmask_b32_e32 v66, v65, v64, vcc
	v_mul_f32_e32 v64, v94, v66
	v_mul_f32_e32 v64, v91, v64
	v_cvt_pk_bf16_f32 v67, v64, s0
	v_lshl_or_b32 v64, v102, 11, v87
	v_mov_b32_e32 v65, v179
	v_lshl_add_u64 v[98:99], v[76:77], 0, v[64:65]
	v_mul_f32_e32 v64, v95, v66
	v_mul_f32_e32 v64, v90, v64
	ds_read_b128 v[68:71], v86 offset:64
	v_cvt_pk_bf16_f32 v64, v64, s0
	global_store_short v[98:99], v64, off offset:64
	v_mul_f32_e32 v64, v97, v66
	v_mul_f32_e32 v64, v93, v64
	v_cvt_pk_bf16_f32 v64, v64, s0
	global_store_short v[98:99], v67, off
	global_store_short v[98:99], v64, off offset:128
	v_mul_f32_e32 v94, v96, v66
	ds_read_b128 v[64:67], v86 offset:96
	s_waitcnt lgkmcnt(1)
	v_rcp_f32_e32 v68, v68
	v_mul_f32_e32 v94, v92, v94
	v_cvt_pk_bf16_f32 v94, v94, s0
	global_store_short v[98:99], v94, off offset:192
	v_mul_f32_e32 v68, v163, v68
	v_mov_b32_e32 v94, v8
	v_mov_b32_e32 v95, v56
	s_waitcnt vmcnt(14)
	v_pk_fma_f32 v[78:79], v[94:95], v[68:69], v[78:79] op_sel_hi:[1,0,1] neg_lo:[1,0,0] neg_hi:[1,0,0]
	v_mov_b32_e32 v96, v24
	v_mov_b32_e32 v97, v40
	v_pk_mul_f32 v[94:95], v[78:79], v[78:79]
	s_waitcnt vmcnt(12)
	v_pk_fma_f32 v[80:81], v[96:97], v[68:69], v[80:81] op_sel_hi:[1,0,1] neg_lo:[1,0,0] neg_hi:[1,0,0]
	v_add_f32_e32 v68, v94, v95
	v_pk_mul_f32 v[96:97], v[80:81], v[80:81]
	v_mov_b32_e32 v98, v25
	v_add_f32_e32 v68, v97, v68
	v_add_f32_e32 v68, v96, v68
	v_mov_b32_e32 v96, v9
	v_mov_b32_e32 v97, v57
	v_add_f32_dpp v68, v68, v68 quad_perm:[1,0,3,2] row_mask:0xf bank_mask:0xf bound_ctrl:1
	v_mov_b32_e32 v99, v41
	global_load_dword v102, v[100:101], off
	global_load_dword v103, v[100:101], off offset:128
	v_add_f32_dpp v68, v68, v68 quad_perm:[2,3,0,1] row_mask:0xf bank_mask:0xf bound_ctrl:1
	v_rcp_f32_e32 v70, v70
	v_rcp_f32_e32 v71, v71
	v_add_f32_dpp v68, v68, v68 row_half_mirror row_mask:0xf bank_mask:0xf bound_ctrl:1
	s_waitcnt lgkmcnt(0)
	v_rcp_f32_e32 v64, v64
	v_rcp_f32_e32 v66, v66
	v_add_f32_dpp v95, v68, v68 row_mirror row_mask:0xf bank_mask:0xf bound_ctrl:1
	v_rcp_f32_e32 v68, v69
	v_mov_b32_e32 v69, v95
	s_nop 1
	v_permlane16_swap_b32_e32 v95, v69
	v_mul_f32_e32 v68, v163, v68
	s_waitcnt vmcnt(12)
	v_pk_fma_f32 v[82:83], v[96:97], v[68:69], v[82:83] op_sel_hi:[1,0,1] neg_lo:[1,0,0] neg_hi:[1,0,0]
	s_waitcnt vmcnt(10)
; __device__ __forceinline__ unsigned f2bf(float f) { return pk2(f, 0.f) & 0xffffu; }
; __device__ __forceinline__ float sum32(float v) { return swap16_sum(sum16(v)); }
; __device__ __forceinline__ int crow(int r, int hi) { return (r & 3) + 8 * (r >> 2) + 4 * hi; }
; __device__ __forceinline__ void attn_unit(const bf16_t* __restrict__ Qb, const bf16_t* __restrict__ Kh, const bf16_t* __restrict__ Vh, int seq, char* lds,
;                                           int mode, float* scratch, float lam, float gscale, const float* __restrict__ subg, bf16_t* outp) {
;     ...
;     bf16_t* ow = outp + (long)(wid * QBLK) * 1024;
;     float g4[4];
; #pragma unroll
;     for (int d0 = 0; d0 < 4; ++d0) g4[d0] = subg[d0 * 32 + r32] * gscale;
; #pragma unroll
;     for (int r = 0; r < 16; ++r) { const int orow = crow(r, hi); const float rl = __builtin_amdgcn_rcpf(li_l[orow]) * lam;
;       float x[4]; float ss = 0.f;
; #pragma unroll
;       for (int d0 = 0; d0 < 4; ++d0) { x[d0] = sw[orow * 128 + d0 * 32 + r32] - o[d0][r] * rl; ss += x[d0] * x[d0]; }
;       ss = sum32(ss);
;       const float rn = rsqrtf(ss * (1.f / 128.f) + 1e-6f);
; #pragma unroll
;       for (int d0 = 0; d0 < 4; ++d0) ow[orow * 1024 + d0 * 32 + r32] = (bf16_t)f2bf(x[d0] * rn * g4[d0]); }
	v_pk_fma_f32 v[84:85], v[98:99], v[68:69], v[84:85] op_sel_hi:[1,0,1] neg_lo:[1,0,0] neg_hi:[1,0,0]
	v_pk_mul_f32 v[96:97], v[82:83], v[82:83]
	global_load_dword v99, v[100:101], off offset:256
	global_load_dword v98, v[100:101], off offset:384
	v_pk_mul_f32 v[100:101], v[84:85], v[84:85]
	v_add_f32_e32 v68, v96, v97
	v_add_f32_e32 v68, v101, v68
	v_add_f32_e32 v68, v100, v68
	v_lshl_or_b32 v96, v108, 9, v88
	v_mov_b32_e32 v97, v179
	v_add_f32_dpp v68, v68, v68 quad_perm:[1,0,3,2] row_mask:0xf bank_mask:0xf bound_ctrl:1
	v_lshl_add_u64 v[96:97], v[72:73], 0, v[96:97]
	global_load_dword v100, v[96:97], off
	global_load_dword v101, v[96:97], off offset:128
	v_add_f32_dpp v68, v68, v68 quad_perm:[2,3,0,1] row_mask:0xf bank_mask:0xf bound_ctrl:1
	v_mul_f32_e32 v64, v163, v64
	s_nop 0
	v_add_f32_dpp v68, v68, v68 row_half_mirror row_mask:0xf bank_mask:0xf bound_ctrl:1
	s_nop 1
	v_add_f32_dpp v94, v68, v68 row_mirror row_mask:0xf bank_mask:0xf bound_ctrl:1
	v_mov_b32_e32 v68, v94
	s_nop 1
	v_permlane16_swap_b32_e32 v94, v68
	v_pk_add_f32 v[68:69], v[94:95], v[68:69]
	v_mov_b32_e32 v95, v179
	v_pk_fma_f32 v[68:69], v[68:69], s[62:63], v[74:75] op_sel_hi:[1,0,0]
	s_nop 0
	v_mul_f32_e32 v94, 0x4b800000, v69
	v_cmp_gt_f32_e32 vcc, s33, v69
	s_nop 1
	v_cndmask_b32_e32 v69, v69, v94, vcc
	v_lshl_or_b32 v94, v104, 11, v87
	global_load_dword v105, v[96:97], off offset:256
	global_load_dword v104, v[96:97], off offset:384
	v_rsq_f32_e32 v69, v69
	v_lshl_add_u64 v[94:95], v[76:77], 0, v[94:95]
	v_mov_b32_e32 v97, v179
	v_mul_f32_e32 v109, 0x45800000, v69
	v_cndmask_b32_e32 v69, v69, v109, vcc
	v_mul_f32_e32 v78, v78, v69
	v_mul_f32_e32 v78, v91, v78
	v_cvt_pk_bf16_f32 v78, v78, s0
	global_store_short v[94:95], v78, off
	v_mul_f32_e32 v78, v79, v69
	v_mul_f32_e32 v78, v90, v78
	v_cvt_pk_bf16_f32 v78, v78, s0
	global_store_short v[94:95], v78, off offset:64
	v_mul_f32_e32 v78, v81, v69
	v_mul_f32_e32 v78, v93, v78
	v_cvt_pk_bf16_f32 v78, v78, s0
	global_store_short v[94:95], v78, off offset:128
	v_mul_f32_e32 v78, 0x4b800000, v68
	v_cmp_gt_f32_e32 vcc, s33, v68
	v_mul_f32_e32 v69, v80, v69
	v_mul_f32_e32 v69, v92, v69
	v_cndmask_b32_e32 v68, v68, v78, vcc
	v_rsq_f32_e32 v68, v68
	v_cvt_pk_bf16_f32 v69, v69, s0
	global_store_short v[94:95], v69, off offset:192
	v_mul_f32_e32 v69, 0x45800000, v68
	v_cndmask_b32_e32 v78, v68, v69, vcc
	v_mul_f32_e32 v68, v82, v78
	v_mul_f32_e32 v68, v91, v68
	v_cvt_pk_bf16_f32 v79, v68, s0
	v_lshl_or_b32 v68, v106, 11, v87
	v_mov_b32_e32 v69, v179
	v_lshl_add_u64 v[68:69], v[76:77], 0, v[68:69]
	global_store_short v[68:69], v79, off
	v_mul_f32_e32 v79, v83, v78
	v_mul_f32_e32 v79, v90, v79
	v_cvt_pk_bf16_f32 v79, v79, s0
	global_store_short v[68:69], v79, off offset:64
	v_mul_f32_e32 v79, v85, v78
	v_mul_f32_e32 v78, v84, v78
	v_mul_f32_e32 v79, v93, v79
	v_mul_f32_e32 v78, v92, v78
	v_cvt_pk_bf16_f32 v79, v79, s0
	v_cvt_pk_bf16_f32 v78, v78, s0
	global_store_short v[68:69], v79, off offset:128
	global_store_short v[68:69], v78, off offset:192
	v_mul_f32_e32 v68, v163, v70
	v_mov_b32_e32 v78, v10
	v_mov_b32_e32 v79, v58
	s_waitcnt vmcnt(14)
	v_pk_fma_f32 v[78:79], v[78:79], v[68:69], v[102:103] op_sel_hi:[1,0,1] neg_lo:[1,0,0] neg_hi:[1,0,0]
	v_mov_b32_e32 v82, v26
	v_mov_b32_e32 v83, v42
	v_pk_mul_f32 v[80:81], v[78:79], v[78:79]
	s_waitcnt vmcnt(12)
	v_pk_fma_f32 v[68:69], v[82:83], v[68:69], v[98:99] op_sel_hi:[1,0,1] neg_lo:[1,0,0] neg_hi:[1,0,0]
	v_add_f32_e32 v70, v80, v81
	v_pk_mul_f32 v[82:83], v[68:69], v[68:69]
	v_or_b32_e32 v106, 24, v89
	v_add_f32_e32 v70, v83, v70
	v_lshl_or_b32 v96, v106, 9, v88
	v_add_f32_e32 v70, v82, v70
	v_lshl_add_u64 v[96:97], v[72:73], 0, v[96:97]
	global_load_dword v98, v[96:97], off
	global_load_dword v99, v[96:97], off offset:128
	v_add_f32_dpp v70, v70, v70 quad_perm:[1,0,3,2] row_mask:0xf bank_mask:0xf bound_ctrl:1
	global_load_dword v103, v[96:97], off offset:256
	global_load_dword v102, v[96:97], off offset:384
	v_add_f32_dpp v70, v70, v70 quad_perm:[2,3,0,1] row_mask:0xf bank_mask:0xf bound_ctrl:1
	v_mul_f32_e32 v80, v163, v71
	v_mov_b32_e32 v84, v11
	v_add_f32_dpp v70, v70, v70 row_half_mirror row_mask:0xf bank_mask:0xf bound_ctrl:1
	v_mov_b32_e32 v85, v59
	s_nop 0
	v_add_f32_dpp v81, v70, v70 row_mirror row_mask:0xf bank_mask:0xf bound_ctrl:1
	v_mov_b32_e32 v83, v81
	s_nop 1
	v_permlane16_swap_b32_e32 v81, v83
	s_waitcnt vmcnt(14)
	v_pk_fma_f32 v[84:85], v[84:85], v[80:81], v[100:101] op_sel_hi:[1,0,1] neg_lo:[1,0,0] neg_hi:[1,0,0]
	v_mov_b32_e32 v100, v27
	v_mov_b32_e32 v101, v43
	v_pk_mul_f32 v[94:95], v[84:85], v[84:85]
	s_waitcnt vmcnt(12)
; __device__ __forceinline__ unsigned f2bf(float f) { return pk2(f, 0.f) & 0xffffu; }
; __device__ __forceinline__ float sum32(float v) { return swap16_sum(sum16(v)); }
; __device__ __forceinline__ int crow(int r, int hi) { return (r & 3) + 8 * (r >> 2) + 4 * hi; }
; __device__ __forceinline__ void attn_unit(const bf16_t* __restrict__ Qb, const bf16_t* __restrict__ Kh, const bf16_t* __restrict__ Vh, int seq, char* lds,
;                                           int mode, float* scratch, float lam, float gscale, const float* __restrict__ subg, bf16_t* outp) {
;     ...
;     bf16_t* ow = outp + (long)(wid * QBLK) * 1024;
;     float g4[4];
; #pragma unroll
;     for (int d0 = 0; d0 < 4; ++d0) g4[d0] = subg[d0 * 32 + r32] * gscale;
; #pragma unroll
;     for (int r = 0; r < 16; ++r) { const int orow = crow(r, hi); const float rl = __builtin_amdgcn_rcpf(li_l[orow]) * lam;
;       float x[4]; float ss = 0.f;
; #pragma unroll
;       for (int d0 = 0; d0 < 4; ++d0) { x[d0] = sw[orow * 128 + d0 * 32 + r32] - o[d0][r] * rl; ss += x[d0] * x[d0]; }
;       ss = sum32(ss);
;       const float rn = rsqrtf(ss * (1.f / 128.f) + 1e-6f);
; #pragma unroll
;       for (int d0 = 0; d0 < 4; ++d0) ow[orow * 1024 + d0 * 32 + r32] = (bf16_t)f2bf(x[d0] * rn * g4[d0]); }
	v_pk_fma_f32 v[96:97], v[100:101], v[80:81], v[104:105] op_sel_hi:[1,0,1] neg_lo:[1,0,0] neg_hi:[1,0,0]
	v_add_f32_e32 v71, v94, v95
	v_pk_mul_f32 v[100:101], v[96:97], v[96:97]
	v_or_b32_e32 v104, 25, v89
	v_add_f32_e32 v71, v101, v71
	v_add_f32_e32 v71, v100, v71
	v_lshl_or_b32 v94, v104, 9, v88
	v_mov_b32_e32 v95, v179
	v_add_f32_dpp v71, v71, v71 quad_perm:[1,0,3,2] row_mask:0xf bank_mask:0xf bound_ctrl:1
	v_lshl_add_u64 v[94:95], v[72:73], 0, v[94:95]
	global_load_dword v100, v[94:95], off
	global_load_dword v101, v[94:95], off offset:128
	v_add_f32_dpp v71, v71, v71 quad_perm:[2,3,0,1] row_mask:0xf bank_mask:0xf bound_ctrl:1
	v_lshl_or_b32 v70, v107, 11, v87
	s_nop 0
	v_add_f32_dpp v71, v71, v71 row_half_mirror row_mask:0xf bank_mask:0xf bound_ctrl:1
	s_nop 1
	v_add_f32_dpp v80, v71, v71 row_mirror row_mask:0xf bank_mask:0xf bound_ctrl:1
	v_mov_b32_e32 v82, v80
	s_nop 1
	v_permlane16_swap_b32_e32 v80, v82
	v_pk_add_f32 v[80:81], v[80:81], v[82:83]
	global_load_dword v83, v[94:95], off offset:256
	global_load_dword v82, v[94:95], off offset:384
	v_pk_fma_f32 v[80:81], v[80:81], s[62:63], v[74:75] op_sel_hi:[1,0,0]
	v_mov_b32_e32 v95, v45
	v_mul_f32_e32 v71, 0x4b800000, v81
	v_cmp_gt_f32_e32 vcc, s33, v81
	s_nop 1
	v_cndmask_b32_e32 v71, v81, v71, vcc
	v_rsq_f32_e32 v81, v71
	v_mov_b32_e32 v71, v179
	v_lshl_add_u64 v[70:71], v[76:77], 0, v[70:71]
	v_mul_f32_e32 v94, 0x45800000, v81
	v_cndmask_b32_e32 v81, v81, v94, vcc
	v_mul_f32_e32 v69, v69, v81
	v_mul_f32_e32 v69, v93, v69
	v_cvt_pk_bf16_f32 v69, v69, s0
	global_store_short v[70:71], v69, off offset:128
	v_mul_f32_e32 v69, 0x4b800000, v80
	v_cmp_gt_f32_e32 vcc, s33, v80
	v_mul_f32_e32 v78, v78, v81
	v_mul_f32_e32 v78, v91, v78
	v_cndmask_b32_e32 v69, v80, v69, vcc
	v_rsq_f32_e32 v69, v69
	v_cvt_pk_bf16_f32 v78, v78, s0
	v_mul_f32_e32 v68, v68, v81
	global_store_short v[70:71], v78, off
	v_mul_f32_e32 v78, v79, v81
	v_mul_f32_e32 v68, v92, v68
	v_mul_f32_e32 v78, v90, v78
	v_cvt_pk_bf16_f32 v68, v68, s0
	v_cvt_pk_bf16_f32 v78, v78, s0
	global_store_short v[70:71], v68, off offset:192
	v_mul_f32_e32 v68, 0x45800000, v69
	global_store_short v[70:71], v78, off offset:64
	v_cndmask_b32_e32 v70, v69, v68, vcc
	v_mul_f32_e32 v68, v84, v70
	v_mul_f32_e32 v68, v91, v68
	v_cvt_pk_bf16_f32 v71, v68, s0
	v_lshl_or_b32 v68, v108, 11, v87
	v_mov_b32_e32 v69, v179
	v_lshl_add_u64 v[68:69], v[76:77], 0, v[68:69]
	global_store_short v[68:69], v71, off
	v_mul_f32_e32 v71, v85, v70
	v_mul_f32_e32 v71, v90, v71
	v_cvt_pk_bf16_f32 v71, v71, s0
	global_store_short v[68:69], v71, off offset:64
	v_mul_f32_e32 v71, v97, v70
	v_mul_f32_e32 v70, v96, v70
	v_mul_f32_e32 v71, v93, v71
	v_mul_f32_e32 v70, v92, v70
	v_cvt_pk_bf16_f32 v71, v71, s0
	v_cvt_pk_bf16_f32 v70, v70, s0
	global_store_short v[68:69], v71, off offset:128
	global_store_short v[68:69], v70, off offset:192
	v_mov_b32_e32 v68, v12
	v_mov_b32_e32 v69, v60
	s_waitcnt vmcnt(14)
	v_pk_fma_f32 v[68:69], v[68:69], v[64:65], v[98:99] op_sel_hi:[1,0,1] neg_lo:[1,0,0] neg_hi:[1,0,0]
	v_mov_b32_e32 v78, v28
	v_mov_b32_e32 v79, v44
	v_pk_mul_f32 v[70:71], v[68:69], v[68:69]
	s_waitcnt vmcnt(12)
	v_pk_fma_f32 v[78:79], v[78:79], v[64:65], v[102:103] op_sel_hi:[1,0,1] neg_lo:[1,0,0] neg_hi:[1,0,0]
	v_add_f32_e32 v64, v70, v71
	v_pk_mul_f32 v[80:81], v[78:79], v[78:79]
	v_mov_b32_e32 v97, v179
	v_add_f32_e32 v64, v81, v64
	v_add_f32_e32 v64, v80, v64
	v_mov_b32_e32 v80, v13
	v_mov_b32_e32 v81, v61
	v_add_f32_dpp v64, v64, v64 quad_perm:[1,0,3,2] row_mask:0xf bank_mask:0xf bound_ctrl:1
	v_mov_b32_e32 v94, v29
	s_nop 0
	v_add_f32_dpp v64, v64, v64 quad_perm:[2,3,0,1] row_mask:0xf bank_mask:0xf bound_ctrl:1
	s_nop 1
	v_add_f32_dpp v64, v64, v64 row_half_mirror row_mask:0xf bank_mask:0xf bound_ctrl:1
	s_nop 1
	v_add_f32_dpp v71, v64, v64 row_mirror row_mask:0xf bank_mask:0xf bound_ctrl:1
	v_rcp_f32_e32 v64, v65
	v_mov_b32_e32 v65, v71
	s_nop 1
	v_permlane16_swap_b32_e32 v71, v65
	v_mul_f32_e32 v64, v163, v64
	s_waitcnt vmcnt(10)
	v_pk_fma_f32 v[80:81], v[80:81], v[64:65], v[100:101] op_sel_hi:[1,0,1] neg_lo:[1,0,0] neg_hi:[1,0,0]
	v_or_b32_e32 v100, 26, v89
	v_lshl_or_b32 v96, v100, 9, v88
	v_lshl_add_u64 v[96:97], v[72:73], 0, v[96:97]
	global_load_dword v98, v[96:97], off
	global_load_dword v99, v[96:97], off offset:128
	s_waitcnt vmcnt(10)
; __device__ __forceinline__ unsigned f2bf(float f) { return pk2(f, 0.f) & 0xffffu; }
; __device__ __forceinline__ float sum32(float v) { return swap16_sum(sum16(v)); }
; __device__ __forceinline__ int crow(int r, int hi) { return (r & 3) + 8 * (r >> 2) + 4 * hi; }
; __device__ __forceinline__ void attn_unit(const bf16_t* __restrict__ Qb, const bf16_t* __restrict__ Kh, const bf16_t* __restrict__ Vh, int seq, char* lds,
;                                           int mode, float* scratch, float lam, float gscale, const float* __restrict__ subg, bf16_t* outp) {
;     ...
;     bf16_t* ow = outp + (long)(wid * QBLK) * 1024;
;     float g4[4];
; #pragma unroll
;     for (int d0 = 0; d0 < 4; ++d0) g4[d0] = subg[d0 * 32 + r32] * gscale;
; #pragma unroll
;     for (int r = 0; r < 16; ++r) { const int orow = crow(r, hi); const float rl = __builtin_amdgcn_rcpf(li_l[orow]) * lam;
;       float x[4]; float ss = 0.f;
; #pragma unroll
;       for (int d0 = 0; d0 < 4; ++d0) { x[d0] = sw[orow * 128 + d0 * 32 + r32] - o[d0][r] * rl; ss += x[d0] * x[d0]; }
;       ss = sum32(ss);
;       const float rn = rsqrtf(ss * (1.f / 128.f) + 1e-6f);
; #pragma unroll
;       for (int d0 = 0; d0 < 4; ++d0) ow[orow * 1024 + d0 * 32 + r32] = (bf16_t)f2bf(x[d0] * rn * g4[d0]); }
	v_pk_fma_f32 v[82:83], v[94:95], v[64:65], v[82:83] op_sel_hi:[1,0,1] neg_lo:[1,0,0] neg_hi:[1,0,0]
	global_load_dword v95, v[96:97], off offset:256
	global_load_dword v94, v[96:97], off offset:384
	v_pk_mul_f32 v[84:85], v[80:81], v[80:81]
	v_pk_mul_f32 v[96:97], v[82:83], v[82:83]
	v_add_f32_e32 v64, v84, v85
	v_add_f32_e32 v64, v97, v64
	v_add_f32_e32 v64, v96, v64
	v_or_b32_e32 v96, 27, v89
	v_lshl_or_b32 v84, v96, 9, v88
	v_add_f32_dpp v64, v64, v64 quad_perm:[1,0,3,2] row_mask:0xf bank_mask:0xf bound_ctrl:1
	v_mov_b32_e32 v85, v179
	v_lshl_add_u64 v[84:85], v[72:73], 0, v[84:85]
	v_add_f32_dpp v64, v64, v64 quad_perm:[2,3,0,1] row_mask:0xf bank_mask:0xf bound_ctrl:1
	global_load_dword v88, v[84:85], off
	global_load_dword v89, v[84:85], off offset:128
	v_add_f32_dpp v64, v64, v64 row_half_mirror row_mask:0xf bank_mask:0xf bound_ctrl:1
	s_nop 1
	v_add_f32_dpp v70, v64, v64 row_mirror row_mask:0xf bank_mask:0xf bound_ctrl:1
	v_mov_b32_e32 v64, v70
	s_nop 1
	v_permlane16_swap_b32_e32 v70, v64
	v_pk_add_f32 v[64:65], v[70:71], v[64:65]
	global_load_dword v71, v[84:85], off offset:256
	global_load_dword v70, v[84:85], off offset:384
	v_pk_fma_f32 v[64:65], v[64:65], s[62:63], v[74:75] op_sel_hi:[1,0,0]
	v_mov_b32_e32 v85, v179
	v_mul_f32_e32 v84, 0x4b800000, v65
	v_cmp_gt_f32_e32 vcc, s33, v65
	s_nop 1
	v_cndmask_b32_e32 v65, v65, v84, vcc
	v_rsq_f32_e32 v65, v65
	v_lshl_or_b32 v84, v106, 11, v87
	v_lshl_add_u64 v[84:85], v[76:77], 0, v[84:85]
	v_mul_f32_e32 v97, 0x45800000, v65
	v_cndmask_b32_e32 v65, v65, v97, vcc
	v_mul_f32_e32 v68, v68, v65
	v_mul_f32_e32 v68, v91, v68
	v_cvt_pk_bf16_f32 v68, v68, s0
	global_store_short v[84:85], v68, off
	v_mul_f32_e32 v68, v69, v65
	v_mul_f32_e32 v68, v90, v68
	v_cvt_pk_bf16_f32 v68, v68, s0
	global_store_short v[84:85], v68, off offset:64
	v_mul_f32_e32 v68, v79, v65
	v_mul_f32_e32 v68, v93, v68
	v_cvt_pk_bf16_f32 v68, v68, s0
	global_store_short v[84:85], v68, off offset:128
	v_mul_f32_e32 v68, 0x4b800000, v64
	v_cmp_gt_f32_e32 vcc, s33, v64
	v_mul_f32_e32 v65, v78, v65
	v_mul_f32_e32 v65, v92, v65
	v_cndmask_b32_e32 v64, v64, v68, vcc
	v_rsq_f32_e32 v64, v64
	v_cvt_pk_bf16_f32 v65, v65, s0
	global_store_short v[84:85], v65, off offset:192
	v_mov_b32_e32 v84, v31
	v_mul_f32_e32 v65, 0x45800000, v64
	v_cndmask_b32_e32 v68, v64, v65, vcc
	v_mul_f32_e32 v64, v80, v68
	v_mul_f32_e32 v64, v91, v64
	v_cvt_pk_bf16_f32 v69, v64, s0
	v_lshl_or_b32 v64, v104, 11, v87
	v_mov_b32_e32 v65, v179
	v_lshl_add_u64 v[64:65], v[76:77], 0, v[64:65]
	global_store_short v[64:65], v69, off
	v_mul_f32_e32 v69, v81, v68
	v_mul_f32_e32 v69, v90, v69
	v_cvt_pk_bf16_f32 v69, v69, s0
	global_store_short v[64:65], v69, off offset:64
	v_mul_f32_e32 v69, v83, v68
	v_mul_f32_e32 v68, v82, v68
	v_mul_f32_e32 v69, v93, v69
	v_mul_f32_e32 v68, v92, v68
	v_cvt_pk_bf16_f32 v69, v69, s0
	v_cvt_pk_bf16_f32 v68, v68, s0
	global_store_short v[64:65], v69, off offset:128
	global_store_short v[64:65], v68, off offset:192
	v_mul_f32_e32 v64, v163, v66
	v_mov_b32_e32 v68, v14
	v_mov_b32_e32 v69, v62
	s_waitcnt vmcnt(14)
	v_pk_fma_f32 v[68:69], v[68:69], v[64:65], v[98:99] op_sel_hi:[1,0,1] neg_lo:[1,0,0] neg_hi:[1,0,0]
	v_mov_b32_e32 v80, v30
	v_mov_b32_e32 v81, v46
	v_pk_mul_f32 v[78:79], v[68:69], v[68:69]
	s_waitcnt vmcnt(12)
	v_pk_fma_f32 v[64:65], v[80:81], v[64:65], v[94:95] op_sel_hi:[1,0,1] neg_lo:[1,0,0] neg_hi:[1,0,0]
	v_add_f32_e32 v66, v78, v79
	v_pk_mul_f32 v[80:81], v[64:65], v[64:65]
	v_mov_b32_e32 v85, v47
	v_add_f32_e32 v66, v81, v66
	v_add_f32_e32 v66, v80, v66
	v_mov_b32_e32 v80, v15
	v_mov_b32_e32 v81, v63
	v_add_f32_dpp v66, v66, v66 quad_perm:[1,0,3,2] row_mask:0xf bank_mask:0xf bound_ctrl:1
	s_nop 1
	v_add_f32_dpp v66, v66, v66 quad_perm:[2,3,0,1] row_mask:0xf bank_mask:0xf bound_ctrl:1
	s_nop 1
	v_add_f32_dpp v66, v66, v66 row_half_mirror row_mask:0xf bank_mask:0xf bound_ctrl:1
	s_nop 1
	v_add_f32_dpp v79, v66, v66 row_mirror row_mask:0xf bank_mask:0xf bound_ctrl:1
	v_rcp_f32_e32 v66, v67
	v_mov_b32_e32 v67, v79
	s_nop 1
	v_permlane16_swap_b32_e32 v79, v67
	v_mul_f32_e32 v66, v163, v66
	s_waitcnt vmcnt(10)
	v_pk_fma_f32 v[80:81], v[80:81], v[66:67], v[88:89] op_sel_hi:[1,0,1] neg_lo:[1,0,0] neg_hi:[1,0,0]
	s_waitcnt vmcnt(8)
	v_pk_fma_f32 v[70:71], v[84:85], v[66:67], v[70:71] op_sel_hi:[1,0,1] neg_lo:[1,0,0] neg_hi:[1,0,0]
	v_pk_mul_f32 v[82:83], v[80:81], v[80:81]
	v_pk_mul_f32 v[84:85], v[70:71], v[70:71]
	v_add_f32_e32 v66, v82, v83
	v_add_f32_e32 v66, v85, v66
	v_add_f32_e32 v66, v84, v66
	s_nop 1
	v_add_f32_dpp v66, v66, v66 quad_perm:[1,0,3,2] row_mask:0xf bank_mask:0xf bound_ctrl:1
	s_nop 1
	v_add_f32_dpp v66, v66, v66 quad_perm:[2,3,0,1] row_mask:0xf bank_mask:0xf bound_ctrl:1
	s_nop 1
	v_add_f32_dpp v66, v66, v66 row_half_mirror row_mask:0xf bank_mask:0xf bound_ctrl:1
	s_nop 1
	v_add_f32_dpp v78, v66, v66 row_mirror row_mask:0xf bank_mask:0xf bound_ctrl:1
	v_mov_b32_e32 v66, v78
	s_nop 1
	v_permlane16_swap_b32_e32 v78, v66
	v_pk_add_f32 v[66:67], v[78:79], v[66:67]
	s_nop 0
	v_pk_fma_f32 v[66:67], v[66:67], s[62:63], v[74:75] op_sel_hi:[1,0,0]
	v_mov_b32_e32 v75, v179
	v_mul_f32_e32 v74, 0x4b800000, v67
	v_cmp_gt_f32_e32 vcc, s33, v67
	s_nop 1
	v_cndmask_b32_e32 v67, v67, v74, vcc
	v_rsq_f32_e32 v67, v67
	v_lshl_or_b32 v74, v100, 11, v87
	v_lshl_add_u64 v[74:75], v[76:77], 0, v[74:75]
	v_mul_f32_e32 v78, 0x45800000, v67
	v_cndmask_b32_e32 v67, v67, v78, vcc
	v_mul_f32_e32 v65, v65, v67
	v_mul_f32_e32 v65, v93, v65
	v_cvt_pk_bf16_f32 v65, v65, s0
	global_store_short v[74:75], v65, off offset:128
	v_mul_f32_e32 v65, 0x4b800000, v66
	v_cmp_gt_f32_e32 vcc, s33, v66
	v_mul_f32_e32 v64, v64, v67
	v_mul_f32_e32 v64, v92, v64
	v_cndmask_b32_e32 v65, v66, v65, vcc
	v_rsq_f32_e32 v65, v65
	v_cvt_pk_bf16_f32 v64, v64, s0
	v_mul_f32_e32 v68, v68, v67
	global_store_short v[74:75], v64, off offset:192
	v_mul_f32_e32 v64, 0x45800000, v65
	v_mul_f32_e32 v68, v91, v68
	v_cndmask_b32_e32 v66, v65, v64, vcc
	v_cvt_pk_bf16_f32 v68, v68, s0
	v_mul_f32_e32 v64, v80, v66
	global_store_short v[74:75], v68, off
	v_mul_f32_e32 v68, v69, v67
	v_mul_f32_e32 v64, v91, v64
	v_mul_f32_e32 v68, v90, v68
	v_cvt_pk_bf16_f32 v67, v64, s0
	v_lshl_or_b32 v64, v96, 11, v87
	v_mov_b32_e32 v65, v179
	v_cvt_pk_bf16_f32 v68, v68, s0
	v_lshl_add_u64 v[64:65], v[76:77], 0, v[64:65]
	global_store_short v[74:75], v68, off offset:64
	global_store_short v[64:65], v67, off
	v_mul_f32_e32 v67, v81, v66
	v_mul_f32_e32 v67, v90, v67
	v_cvt_pk_bf16_f32 v67, v67, s0
	global_store_short v[64:65], v67, off offset:64
	v_mul_f32_e32 v67, v71, v66
	v_mul_f32_e32 v66, v70, v66
	v_mul_f32_e32 v67, v93, v67
	v_mul_f32_e32 v66, v92, v66
	v_cvt_pk_bf16_f32 v67, v67, s0
	v_cvt_pk_bf16_f32 v66, v66, s0
	global_store_short v[64:65], v67, off offset:128
	global_store_short v[64:65], v66, off offset:192
